# P0 table-acquire invalidate hoisted before the workgroup barrier + in-proj last-round epilogue stores write-through (sc1)
# baseline (speedup 1.0000x reference)
; __device__ __forceinline__ void p0_phase(const Args& a, LAS unsigned char* lds, int tid, int lane, int wave, int bid, int G) {
;     ...
;     if (bid < 192 || G < 192) {
;         if (tid == 0) {
;             unsigned sp = 0;
;             while (__hip_atomic_load(flag, __ATOMIC_RELAXED, __HIP_MEMORY_SCOPE_AGENT) < (unsigned)nprod) { __builtin_amdgcn_s_sleep(2); if (++sp > (1u << 22)) break; }
;             __builtin_amdgcn_fence(__ATOMIC_ACQUIRE, "agent"); asm volatile("s_waitcnt vmcnt(0)" ::: "memory");
.LBB0_60:
	s_cmpk_lt_i32 s71, 0xc0
	s_cselect_b64 s[0:1], -1, 0
	s_cbranch_scc0 .Lp0inv_skip
	v_cmp_eq_u32_e32 vcc, 0, v114
	s_and_saveexec_b64 s[4:5], vcc
	s_cbranch_execz .Lp0inv_none
	buffer_inv sc1

; __device__ __forceinline__ void p0_phase(const Args& a, LAS unsigned char* lds, int tid, int lane, int wave, int bid, int G) {
;     ...
;     if (bid < 192 || G < 192) {
;         if (tid == 0) {
;             unsigned sp = 0;
;             while (__hip_atomic_load(flag, __ATOMIC_RELAXED, __HIP_MEMORY_SCOPE_AGENT) < (unsigned)nprod) { __builtin_amdgcn_s_sleep(2); if (++sp > (1u << 22)) break; }
;             __builtin_amdgcn_fence(__ATOMIC_ACQUIRE, "agent"); asm volatile("s_waitcnt vmcnt(0)" ::: "memory");
.Lp0inv_skip:
	s_min_i32 s4, s71, s42
	s_cmpk_gt_i32 s4, 0xbf
	s_barrier
	s_cbranch_scc1 .LBB0_123
	v_cmp_eq_u32_e32 vcc, 0, v114
	s_and_saveexec_b64 s[4:5], vcc
	s_cbranch_execz .LBB0_71
	s_mov_b32 s8, 0x400001
	v_mov_b32_e32 v0, 0
	s_branch .LBB0_64

; __device__ __forceinline__ void p0_mod_item(const Args& a, LAS unsigned char* lds, int it, int tid, int lane, int wave) {
;     const int l = it / 96, col0 = (it % 96) * 32;
;     const float* W = a.in[7] + (size_t)l * D * 3072;
;     const int n = lane & 31, kq = lane >> 5;
;     f32x16 acc[5];
; #pragma unroll
;     for (int rt = 0; rt < 5; ++rt)
; #pragma unroll
;         for (int i = 0; i < 16; ++i) acc[rt][i] = 0.f;
;     const u32x4* tabs = (const u32x4*)(a.ws + WS_SILU) + (size_t)(wave * 8) * 64 + lane;
;     const float* wp = W + (size_t)(wave * 128 + 8 * kq) * 3072 + col0 + n;
; __device__ __forceinline__ void p0_phase(const Args& a, LAS unsigned char* lds, int tid, int lane, int wave, int bid, int G) {
;     ...
;             while (__hip_atomic_load(flag, __ATOMIC_RELAXED, __HIP_MEMORY_SCOPE_AGENT) < (unsigned)nprod) { __builtin_amdgcn_s_sleep(2); if (++sp > (1u << 22)) break; }
;             __builtin_amdgcn_fence(__ATOMIC_ACQUIRE, "agent"); asm volatile("s_waitcnt vmcnt(0)" ::: "memory");
;         }
;         __syncthreads();
;         asm volatile("" : "+v"(tid)); lane = tid & 63;
;         for (int it = bid; it < 192; it += G) p0_mod_item(a, lds, it, tid, lane, wave);
.LBB0_64:
	global_load_dword v1, v0, s[10:11] sc1
	s_mov_b64 s[6:7], -1
	s_waitcnt vmcnt(0)
	v_cmp_le_u32_e32 vcc, s23, v1
	s_cbranch_vccnz .LBB0_63
	s_sleep 2
	global_load_dword v1, v0, s[10:11] sc1
	s_waitcnt vmcnt(0)
	v_cmp_gt_u32_e32 vcc, s23, v1
	s_cbranch_vccz .LBB0_63
	s_sleep 2
	global_load_dword v1, v0, s[10:11] sc1
	s_waitcnt vmcnt(0)
	v_cmp_gt_u32_e32 vcc, s23, v1
	s_cbranch_vccz .LBB0_63
	s_sleep 2
	global_load_dword v1, v0, s[10:11] sc1
	s_waitcnt vmcnt(0)
	v_cmp_gt_u32_e32 vcc, s23, v1
	s_cbranch_vccz .LBB0_63
	s_sleep 2
	global_load_dword v1, v0, s[10:11] sc1
	s_waitcnt vmcnt(0)
	v_cmp_gt_u32_e32 vcc, s23, v1
	s_cbranch_vccz .LBB0_63
	s_add_i32 s8, s8, -5
	s_cmp_eq_u32 s8, 0
	s_cselect_b64 s[6:7], -1, 0
	s_sleep 2
	s_branch .LBB0_63
.LBB0_70:
	s_waitcnt vmcnt(0)
.LBB0_71:
	s_or_b64 exec, exec, s[4:5]
	s_andn2_b64 vcc, exec, s[0:1]
	s_barrier
	s_cbranch_vccnz .LBB0_123
	v_readlane_b32 s4, v253, 4
	s_lshl_b32 s0, s3, 3
	v_readlane_b32 s5, v253, 5
	s_ashr_i32 s1, s0, 31
	s_lshl_b64 s[4:5], s[0:1], 10
	s_lshl_b32 s0, s3, 7
	v_readlane_b32 s6, v253, 6
	v_readlane_b32 s7, v253, 7
	s_cmp_gt_u32 s22, 63
	v_and_b32_e32 v3, 63, v114
	v_and_b32_e32 v80, 31, v114
	v_bfe_u32 v2, v114, 5, 1
	s_cselect_b64 s[6:7], -1, 0
	s_add_u32 s4, s78, s4
	v_readlane_b32 s18, v253, 18
	v_readlane_b32 s19, v253, 19
	v_lshl_or_b32 v6, v2, 3, s0
	v_mov_b32_e32 v83, 0
	v_lshlrev_b32_e32 v4, 9, v2
	v_lshlrev_b32_e32 v2, 2, v80
	s_addc_u32 s5, s79, s5
	v_lshlrev_b32_e32 v82, 4, v3
	v_mov_b32_e32 v0, s18
	v_mov_b32_e32 v1, s19
	v_add3_u32 v81, 0, v4, v2
	v_lshl_add_u64 v[4:5], s[4:5], 0, v[82:83]
	s_mov_b64 s[4:5], 0x1680000
	s_movk_i32 s22, 0x3000
	v_lshl_add_u64 v[84:85], v[4:5], 0, s[4:5]
	v_mad_i64_i32 v[86:87], s[4:5], v6, s22, v[0:1]
	v_mov_b32_e32 v3, v83
	v_readlane_b32 s8, v253, 8
	v_readlane_b32 s9, v253, 9
	v_readlane_b32 s10, v253, 10
	v_readlane_b32 s11, v253, 11
	v_readlane_b32 s12, v253, 12
	v_readlane_b32 s13, v253, 13
	v_readlane_b32 s14, v253, 14
	v_readlane_b32 s15, v253, 15
	v_readlane_b32 s16, v253, 16
	v_readlane_b32 s17, v253, 17
	s_movk_i32 s0, 0x1080
	v_lshl_add_u64 v[0:1], s[78:79], 0, v[2:3]
	s_mov_b64 s[4:5], 0x1200000
	v_cmp_gt_i32_e64 s[0:1], s0, v114
	v_lshl_add_u64 v[88:89], v[0:1], 0, s[4:5]
	v_lshl_add_u32 v94, v114, 2, 0
	v_mov_b32_e32 v95, 0xc00000
	v_lshlrev_b32_e32 v82, 2, v80
	s_movk_i32 s23, 0x6000
	s_mov_b32 s24, 0x9000
	s_mov_b32 s25, 0xc000
	s_mov_b32 s26, 0xf000
	s_mov_b32 s27, 0x12000
	s_mov_b32 s28, 0x15000
	s_mov_b64 s[8:9], 0x10000
	s_mov_b32 s29, 0x10000
	s_mov_b64 s[10:11], 0x20000
	s_mov_b32 s30, 0x20000
	s_mov_b64 s[12:13], 0x30000
	s_mov_b32 s31, 0x30000
	s_mov_b64 s[14:15], 0x40000
	s_mov_b32 s33, 0x40000
	s_mov_b32 s34, 0x33000
	s_mov_b32 s35, 0x36000
	s_mov_b32 s36, 0x39000
	s_mov_b32 s37, 0x3c000
	s_mov_b32 s38, 0x3f000
	s_mov_b32 s39, 0x42000
	s_mov_b32 s40, 0x45000
	s_mov_b64 s[16:17], 0x60000
	s_movk_i32 s41, 0xe7f
	s_mov_b32 s44, s71
	s_branch .LBB0_74

; __device__ __forceinline__ unsigned cvt_pk_bf16(float lo, float hi) { unsigned r; asm volatile("v_cvt_pk_bf16_f32 %0, %1, %2" : "=v"(r) : "v"(lo), "v"(hi)); return r; }
; __device__ __forceinline__ float silu_f(float v) { return v * __builtin_amdgcn_rcpf(1.0f + __builtin_amdgcn_exp2f(-v * LOG2E_)); }
;     __device__ __forceinline__ void operator()(const f32x4 (&acc)[2][2][4][2], const Unit& u, int wr, int wc, int fr, int fq) const {
;     ...
;         if (u.pn < 8) {
;             const bool bz = u.pn >= 4;
;             const int col0 = (bz ? 512 + (u.pn - 4) * 128 : u.pn * 128) + wc * 32 + 8 * fq;
; #pragma unroll
;             for (int ai = 0; ai < 2; ++ai)
; #pragma unroll
;                 for (int m = 0; m < 4; ++m) {
;                     const f32x4 a0 = acc[ai][0][m][0], a1 = acc[ai][0][m][1], b0 = acc[ai][1][m][0], b1 = acc[ai][1][m][1];
;                     f32x4 v0, v1;
;                     if (bz) { v0 = (f32x4){a0[0] * silu_f(b0[0]), a0[1] * silu_f(b0[1]), a0[2] * silu_f(b0[2]), a0[3] * silu_f(b0[3])};
;                               v1 = (f32x4){a1[0] * silu_f(b1[0]), a1[1] * silu_f(b1[1]), a1[2] * silu_f(b1[2]), a1[3] * silu_f(b1[3])}; }
;                     else { v0 = a0 * b0; v1 = a1 * b1; }
;                     u32x4 w; w.x = cvt_pk_bf16(v0[0], v0[1]); w.y = cvt_pk_bf16(v0[2], v0[3]); w.z = cvt_pk_bf16(v1[0], v1[1]); w.w = cvt_pk_bf16(v1[2], v1[3]);
;                     *(u32x4*)(O + (size_t)(row0 + ai * HALF + m * 16) * PO2 + col0) = w;
;                 }
.LBB0_280:
	v_pk_mul_f32 v[116:117], v[124:125], v[116:117]
	v_lshl_or_b32 v140, s18, 7, v152
	v_pk_mul_f32 v[118:119], v[126:127], v[118:119]
	v_pk_mul_f32 v[122:123], v[122:123], v[114:115]
	v_pk_mul_f32 v[114:115], v[120:121], v[112:113]
	v_cvt_pk_bf16_f32 v112, v116, v117
	v_mov_b64_e32 v[116:117], s[74:75]
	v_ashrrev_i32_e32 v141, 31, v140
	v_cvt_pk_bf16_f32 v113, v118, v119
	v_mad_i64_i32 v[116:117], s[4:5], v155, s97, v[116:117]
	v_cndmask_b32_e64 v118, 0, 1, s[20:21]
	v_lshl_add_u64 v[116:117], v[140:141], 1, v[116:117]
	v_cmp_ne_u32_e64 s[4:5], 1, v118
	s_andn2_b64 vcc, exec, s[20:21]
	v_cvt_pk_bf16_f32 v114, v114, v115
	v_cvt_pk_bf16_f32 v115, v122, v123
	s_cmp_eq_u32 s34, 4
	s_cbranch_scc1 .Lwt3_0
	global_store_dwordx4 v[116:117], v[112:115], off
	s_branch .Lwj3_0
.Lwt3_0:
	global_store_dwordx4 v[116:117], v[112:115], off sc1
.Lwj3_0:
	s_cbranch_vccnz .LBB0_282
	s_nop 0
	v_mul_f32_e32 v112, 0xbfb8aa3b, v100
	v_mul_f32_e32 v113, 0xbfb8aa3b, v101
	v_mul_f32_e32 v114, 0xbfb8aa3b, v102
	v_mul_f32_e32 v115, 0xbfb8aa3b, v103
	v_exp_f32_e32 v112, v112
	v_exp_f32_e32 v113, v113
	v_exp_f32_e32 v114, v114
	v_exp_f32_e32 v115, v115
	v_add_f32_e32 v112, 1.0, v112
	v_add_f32_e32 v113, 1.0, v113
	v_add_f32_e32 v114, 1.0, v114
	v_add_f32_e32 v115, 1.0, v115
	v_rcp_f32_e32 v112, v112
	v_rcp_f32_e32 v113, v113
	v_rcp_f32_e32 v114, v114
	v_rcp_f32_e32 v115, v115
	v_pk_mul_f32 v[100:101], v[100:101], v[112:113]
	v_mul_f32_e32 v112, 0xbfb8aa3b, v96
	v_pk_mul_f32 v[102:103], v[102:103], v[114:115]
	v_mul_f32_e32 v113, 0xbfb8aa3b, v97
	v_mul_f32_e32 v114, 0xbfb8aa3b, v98
	v_mul_f32_e32 v115, 0xbfb8aa3b, v99
	v_exp_f32_e32 v112, v112
	v_exp_f32_e32 v113, v113
	v_exp_f32_e32 v114, v114
	v_exp_f32_e32 v115, v115
	v_add_f32_e32 v112, 1.0, v112
	v_add_f32_e32 v113, 1.0, v113
	v_add_f32_e32 v114, 1.0, v114
	v_add_f32_e32 v115, 1.0, v115
	v_rcp_f32_e32 v112, v112
	v_rcp_f32_e32 v113, v113
	v_rcp_f32_e32 v114, v114
	v_rcp_f32_e32 v115, v115
	v_pk_mul_f32 v[96:97], v[96:97], v[112:113]
	v_pk_mul_f32 v[98:99], v[98:99], v[114:115]
.LBB0_282:
	v_pk_mul_f32 v[102:103], v[110:111], v[102:103]
	v_pk_mul_f32 v[100:101], v[108:109], v[100:101]
	v_pk_mul_f32 v[106:107], v[106:107], v[98:99]
	v_pk_mul_f32 v[98:99], v[104:105], v[96:97]
	v_cvt_pk_bf16_f32 v96, v100, v101
	v_cvt_pk_bf16_f32 v97, v102, v103
	v_or_b32_e32 v102, 16, v155
	v_mov_b64_e32 v[100:101], s[74:75]
	v_mad_i64_i32 v[100:101], s[20:21], v102, s97, v[100:101]
	v_lshl_add_u64 v[100:101], v[140:141], 1, v[100:101]
	s_and_b64 vcc, exec, s[4:5]
	v_cvt_pk_bf16_f32 v98, v98, v99
	v_cvt_pk_bf16_f32 v99, v106, v107
	s_cmp_eq_u32 s34, 4
	s_cbranch_scc1 .Lwt3_1
	global_store_dwordx4 v[100:101], v[96:99], off
	s_branch .Lwj3_1
.Lwt3_1:
	global_store_dwordx4 v[100:101], v[96:99], off sc1
.Lwj3_1:
	s_cbranch_vccnz .LBB0_284
	s_nop 0
	v_mul_f32_e32 v96, 0xbfb8aa3b, v84
	v_mul_f32_e32 v97, 0xbfb8aa3b, v85
	v_mul_f32_e32 v98, 0xbfb8aa3b, v86
	v_mul_f32_e32 v99, 0xbfb8aa3b, v87
	v_exp_f32_e32 v96, v96
	v_exp_f32_e32 v97, v97
	v_exp_f32_e32 v98, v98
	v_exp_f32_e32 v99, v99
	v_add_f32_e32 v96, 1.0, v96
	v_add_f32_e32 v97, 1.0, v97
	v_add_f32_e32 v98, 1.0, v98
	v_add_f32_e32 v99, 1.0, v99
	v_rcp_f32_e32 v96, v96
	v_rcp_f32_e32 v97, v97
	v_rcp_f32_e32 v98, v98
	v_rcp_f32_e32 v99, v99
	v_pk_mul_f32 v[84:85], v[84:85], v[96:97]
	v_mul_f32_e32 v96, 0xbfb8aa3b, v80
	v_pk_mul_f32 v[86:87], v[86:87], v[98:99]
	v_mul_f32_e32 v97, 0xbfb8aa3b, v81
	v_mul_f32_e32 v98, 0xbfb8aa3b, v82
	v_mul_f32_e32 v99, 0xbfb8aa3b, v83
	v_exp_f32_e32 v96, v96
	v_exp_f32_e32 v97, v97
	v_exp_f32_e32 v98, v98
	v_exp_f32_e32 v99, v99
	v_add_f32_e32 v96, 1.0, v96
	v_add_f32_e32 v97, 1.0, v97
	v_add_f32_e32 v98, 1.0, v98
	v_add_f32_e32 v99, 1.0, v99
	v_rcp_f32_e32 v96, v96
	v_rcp_f32_e32 v97, v97
	v_rcp_f32_e32 v98, v98
	v_rcp_f32_e32 v99, v99
	v_pk_mul_f32 v[80:81], v[80:81], v[96:97]
	v_pk_mul_f32 v[82:83], v[82:83], v[98:99]
.LBB0_284:
	v_pk_mul_f32 v[86:87], v[94:95], v[86:87]
	v_pk_mul_f32 v[84:85], v[92:93], v[84:85]
	v_pk_mul_f32 v[90:91], v[90:91], v[82:83]
	v_pk_mul_f32 v[82:83], v[88:89], v[80:81]
	v_cvt_pk_bf16_f32 v80, v84, v85
	v_cvt_pk_bf16_f32 v81, v86, v87
	v_or_b32_e32 v86, 32, v155
	v_mov_b64_e32 v[84:85], s[74:75]
	v_mad_i64_i32 v[84:85], s[20:21], v86, s97, v[84:85]
	v_lshl_add_u64 v[84:85], v[140:141], 1, v[84:85]
	s_and_b64 vcc, exec, s[4:5]
	v_cvt_pk_bf16_f32 v82, v82, v83
	v_cvt_pk_bf16_f32 v83, v90, v91
	s_cmp_eq_u32 s34, 4
	s_cbranch_scc1 .Lwt3_2
	global_store_dwordx4 v[84:85], v[80:83], off
	s_branch .Lwj3_2
.Lwt3_2:
	global_store_dwordx4 v[84:85], v[80:83], off sc1
.Lwj3_2:
	s_cbranch_vccnz .LBB0_286
	s_nop 0
	v_mul_f32_e32 v80, 0xbfb8aa3b, v68
	v_mul_f32_e32 v81, 0xbfb8aa3b, v69
	v_mul_f32_e32 v82, 0xbfb8aa3b, v70
	v_mul_f32_e32 v83, 0xbfb8aa3b, v71
	v_exp_f32_e32 v80, v80
	v_exp_f32_e32 v81, v81
	v_exp_f32_e32 v82, v82
	v_exp_f32_e32 v83, v83
	v_add_f32_e32 v80, 1.0, v80
	v_add_f32_e32 v81, 1.0, v81
	v_add_f32_e32 v82, 1.0, v82
	v_add_f32_e32 v83, 1.0, v83
	v_rcp_f32_e32 v80, v80
	v_rcp_f32_e32 v81, v81
	v_rcp_f32_e32 v82, v82
	v_rcp_f32_e32 v83, v83
	v_pk_mul_f32 v[68:69], v[68:69], v[80:81]
	v_mul_f32_e32 v80, 0xbfb8aa3b, v64
	v_pk_mul_f32 v[70:71], v[70:71], v[82:83]
	v_mul_f32_e32 v81, 0xbfb8aa3b, v65
	v_mul_f32_e32 v82, 0xbfb8aa3b, v66
	v_mul_f32_e32 v83, 0xbfb8aa3b, v67
	v_exp_f32_e32 v80, v80
	v_exp_f32_e32 v81, v81
	v_exp_f32_e32 v82, v82
	v_exp_f32_e32 v83, v83
	v_add_f32_e32 v80, 1.0, v80
	v_add_f32_e32 v81, 1.0, v81
	v_add_f32_e32 v82, 1.0, v82
	v_add_f32_e32 v83, 1.0, v83
	v_rcp_f32_e32 v80, v80
	v_rcp_f32_e32 v81, v81
	v_rcp_f32_e32 v82, v82
	v_rcp_f32_e32 v83, v83
	v_pk_mul_f32 v[64:65], v[64:65], v[80:81]
	v_pk_mul_f32 v[66:67], v[66:67], v[82:83]
; __device__ __forceinline__ unsigned cvt_pk_bf16(float lo, float hi) { unsigned r; asm volatile("v_cvt_pk_bf16_f32 %0, %1, %2" : "=v"(r) : "v"(lo), "v"(hi)); return r; }
; __device__ __forceinline__ float silu_f(float v) { return v * __builtin_amdgcn_rcpf(1.0f + __builtin_amdgcn_exp2f(-v * LOG2E_)); }
;     __device__ __forceinline__ void operator()(const f32x4 (&acc)[2][2][4][2], const Unit& u, int wr, int wc, int fr, int fq) const {
;     ...
;                 for (int m = 0; m < 4; ++m) {
;                     const f32x4 a0 = acc[ai][0][m][0], a1 = acc[ai][0][m][1], b0 = acc[ai][1][m][0], b1 = acc[ai][1][m][1];
;                     f32x4 v0, v1;
;                     if (bz) { v0 = (f32x4){a0[0] * silu_f(b0[0]), a0[1] * silu_f(b0[1]), a0[2] * silu_f(b0[2]), a0[3] * silu_f(b0[3])};
;                               v1 = (f32x4){a1[0] * silu_f(b1[0]), a1[1] * silu_f(b1[1]), a1[2] * silu_f(b1[2]), a1[3] * silu_f(b1[3])}; }
;                     else { v0 = a0 * b0; v1 = a1 * b1; }
;                     u32x4 w; w.x = cvt_pk_bf16(v0[0], v0[1]); w.y = cvt_pk_bf16(v0[2], v0[3]); w.z = cvt_pk_bf16(v1[0], v1[1]); w.w = cvt_pk_bf16(v1[2], v1[3]);
;                     *(u32x4*)(O + (size_t)(row0 + ai * HALF + m * 16) * PO2 + col0) = w;
;                 }
.LBB0_286:
	v_pk_mul_f32 v[70:71], v[78:79], v[70:71]
	v_pk_mul_f32 v[68:69], v[76:77], v[68:69]
	v_pk_mul_f32 v[74:75], v[74:75], v[66:67]
	v_pk_mul_f32 v[66:67], v[72:73], v[64:65]
	v_cvt_pk_bf16_f32 v64, v68, v69
	v_cvt_pk_bf16_f32 v65, v70, v71
	v_or_b32_e32 v70, 48, v155
	v_mov_b64_e32 v[68:69], s[74:75]
	v_mad_i64_i32 v[68:69], s[20:21], v70, s97, v[68:69]
	v_lshl_add_u64 v[68:69], v[140:141], 1, v[68:69]
	s_and_b64 vcc, exec, s[4:5]
	v_cvt_pk_bf16_f32 v66, v66, v67
	v_cvt_pk_bf16_f32 v67, v74, v75
	s_cmp_eq_u32 s34, 4
	s_cbranch_scc1 .Lwt3_3
	global_store_dwordx4 v[68:69], v[64:67], off
	s_branch .Lwj3_3
.Lwt3_3:
	global_store_dwordx4 v[68:69], v[64:67], off sc1
.Lwj3_3:
	s_cbranch_vccnz .LBB0_288
	s_nop 0
	v_mul_f32_e32 v64, 0xbfb8aa3b, v52
	v_mul_f32_e32 v65, 0xbfb8aa3b, v53
	v_mul_f32_e32 v66, 0xbfb8aa3b, v54
	v_mul_f32_e32 v67, 0xbfb8aa3b, v55
	v_exp_f32_e32 v64, v64
	v_exp_f32_e32 v65, v65
	v_exp_f32_e32 v66, v66
	v_exp_f32_e32 v67, v67
	v_add_f32_e32 v64, 1.0, v64
	v_add_f32_e32 v65, 1.0, v65
	v_add_f32_e32 v66, 1.0, v66
	v_add_f32_e32 v67, 1.0, v67
	v_rcp_f32_e32 v64, v64
	v_rcp_f32_e32 v65, v65
	v_rcp_f32_e32 v66, v66
	v_rcp_f32_e32 v67, v67
	v_pk_mul_f32 v[52:53], v[52:53], v[64:65]
	v_mul_f32_e32 v64, 0xbfb8aa3b, v48
	v_pk_mul_f32 v[54:55], v[54:55], v[66:67]
	v_mul_f32_e32 v65, 0xbfb8aa3b, v49
	v_mul_f32_e32 v66, 0xbfb8aa3b, v50
	v_mul_f32_e32 v67, 0xbfb8aa3b, v51
	v_exp_f32_e32 v64, v64
	v_exp_f32_e32 v65, v65
	v_exp_f32_e32 v66, v66
	v_exp_f32_e32 v67, v67
	v_add_f32_e32 v64, 1.0, v64
	v_add_f32_e32 v65, 1.0, v65
	v_add_f32_e32 v66, 1.0, v66
	v_add_f32_e32 v67, 1.0, v67
	v_rcp_f32_e32 v64, v64
	v_rcp_f32_e32 v65, v65
	v_rcp_f32_e32 v66, v66
	v_rcp_f32_e32 v67, v67
	v_pk_mul_f32 v[48:49], v[48:49], v[64:65]
	v_pk_mul_f32 v[50:51], v[50:51], v[66:67]
.LBB0_288:
	v_pk_mul_f32 v[52:53], v[60:61], v[52:53]
	v_add_u32_e32 v64, 0x80, v155
	v_pk_mul_f32 v[58:59], v[58:59], v[50:51]
	v_pk_mul_f32 v[50:51], v[56:57], v[48:49]
	v_cvt_pk_bf16_f32 v48, v52, v53
	v_mov_b64_e32 v[52:53], s[74:75]
	v_mad_i64_i32 v[52:53], s[20:21], v64, s97, v[52:53]
	v_lshl_add_u64 v[52:53], v[140:141], 1, v[52:53]
	s_and_b64 vcc, exec, s[4:5]
	v_pk_mul_f32 v[54:55], v[62:63], v[54:55]
	s_nop 0
	v_cvt_pk_bf16_f32 v49, v54, v55
	v_cvt_pk_bf16_f32 v50, v50, v51
	v_cvt_pk_bf16_f32 v51, v58, v59
	s_cmp_eq_u32 s34, 4
	s_cbranch_scc1 .Lwt3_4
	global_store_dwordx4 v[52:53], v[48:51], off
	s_branch .Lwj3_4
.Lwt3_4:
	global_store_dwordx4 v[52:53], v[48:51], off sc1
.Lwj3_4:
	s_cbranch_vccnz .LBB0_290
	s_nop 0
	v_mul_f32_e32 v48, 0xbfb8aa3b, v36
	v_mul_f32_e32 v49, 0xbfb8aa3b, v37
	v_mul_f32_e32 v50, 0xbfb8aa3b, v38
	v_mul_f32_e32 v51, 0xbfb8aa3b, v39
	v_exp_f32_e32 v48, v48
	v_exp_f32_e32 v49, v49
	v_exp_f32_e32 v50, v50
	v_exp_f32_e32 v51, v51
	v_add_f32_e32 v48, 1.0, v48
	v_add_f32_e32 v49, 1.0, v49
	v_add_f32_e32 v50, 1.0, v50
	v_add_f32_e32 v51, 1.0, v51
	v_rcp_f32_e32 v48, v48
	v_rcp_f32_e32 v49, v49
	v_rcp_f32_e32 v50, v50
	v_rcp_f32_e32 v51, v51
	v_pk_mul_f32 v[36:37], v[36:37], v[48:49]
	v_mul_f32_e32 v48, 0xbfb8aa3b, v32
	v_pk_mul_f32 v[38:39], v[38:39], v[50:51]
	v_mul_f32_e32 v49, 0xbfb8aa3b, v33
	v_mul_f32_e32 v50, 0xbfb8aa3b, v34
	v_mul_f32_e32 v51, 0xbfb8aa3b, v35
	v_exp_f32_e32 v48, v48
	v_exp_f32_e32 v49, v49
	v_exp_f32_e32 v50, v50
	v_exp_f32_e32 v51, v51
	v_add_f32_e32 v48, 1.0, v48
	v_add_f32_e32 v49, 1.0, v49
	v_add_f32_e32 v50, 1.0, v50
	v_add_f32_e32 v51, 1.0, v51
	v_rcp_f32_e32 v48, v48
	v_rcp_f32_e32 v49, v49
	v_rcp_f32_e32 v50, v50
	v_rcp_f32_e32 v51, v51
	v_pk_mul_f32 v[32:33], v[32:33], v[48:49]
	v_pk_mul_f32 v[34:35], v[34:35], v[50:51]
.LBB0_290:
	v_pk_mul_f32 v[38:39], v[46:47], v[38:39]
	v_pk_mul_f32 v[36:37], v[44:45], v[36:37]
	v_pk_mul_f32 v[42:43], v[42:43], v[34:35]
	v_pk_mul_f32 v[34:35], v[40:41], v[32:33]
	v_cvt_pk_bf16_f32 v32, v36, v37
	v_cvt_pk_bf16_f32 v33, v38, v39
	v_add_u32_e32 v38, 0x90, v155
	v_mov_b64_e32 v[36:37], s[74:75]
	v_mad_i64_i32 v[36:37], s[20:21], v38, s97, v[36:37]
	v_lshl_add_u64 v[36:37], v[140:141], 1, v[36:37]
	s_and_b64 vcc, exec, s[4:5]
	v_cvt_pk_bf16_f32 v34, v34, v35
	v_cvt_pk_bf16_f32 v35, v42, v43
	s_cmp_eq_u32 s34, 4
	s_cbranch_scc1 .Lwt3_5
	global_store_dwordx4 v[36:37], v[32:35], off
	s_branch .Lwj3_5
; __device__ __forceinline__ unsigned cvt_pk_bf16(float lo, float hi) { unsigned r; asm volatile("v_cvt_pk_bf16_f32 %0, %1, %2" : "=v"(r) : "v"(lo), "v"(hi)); return r; }
; __device__ __forceinline__ float silu_f(float v) { return v * __builtin_amdgcn_rcpf(1.0f + __builtin_amdgcn_exp2f(-v * LOG2E_)); }
;     __device__ __forceinline__ void operator()(const f32x4 (&acc)[2][2][4][2], const Unit& u, int wr, int wc, int fr, int fq) const {
;     ...
;                 for (int m = 0; m < 4; ++m) {
;                     const f32x4 a0 = acc[ai][0][m][0], a1 = acc[ai][0][m][1], b0 = acc[ai][1][m][0], b1 = acc[ai][1][m][1];
;                     f32x4 v0, v1;
;                     if (bz) { v0 = (f32x4){a0[0] * silu_f(b0[0]), a0[1] * silu_f(b0[1]), a0[2] * silu_f(b0[2]), a0[3] * silu_f(b0[3])};
;                               v1 = (f32x4){a1[0] * silu_f(b1[0]), a1[1] * silu_f(b1[1]), a1[2] * silu_f(b1[2]), a1[3] * silu_f(b1[3])}; }
;                     else { v0 = a0 * b0; v1 = a1 * b1; }
;                     u32x4 w; w.x = cvt_pk_bf16(v0[0], v0[1]); w.y = cvt_pk_bf16(v0[2], v0[3]); w.z = cvt_pk_bf16(v1[0], v1[1]); w.w = cvt_pk_bf16(v1[2], v1[3]);
;                     *(u32x4*)(O + (size_t)(row0 + ai * HALF + m * 16) * PO2 + col0) = w;
;                 }
.Lwt3_5:
	global_store_dwordx4 v[36:37], v[32:35], off sc1
.Lwj3_5:
	s_cbranch_vccnz .LBB0_292
	s_nop 0
	v_mul_f32_e32 v32, 0xbfb8aa3b, v20
	v_mul_f32_e32 v33, 0xbfb8aa3b, v21
	v_mul_f32_e32 v34, 0xbfb8aa3b, v22
	v_mul_f32_e32 v35, 0xbfb8aa3b, v23
	v_exp_f32_e32 v32, v32
	v_exp_f32_e32 v33, v33
	v_exp_f32_e32 v34, v34
	v_exp_f32_e32 v35, v35
	v_add_f32_e32 v32, 1.0, v32
	v_add_f32_e32 v33, 1.0, v33
	v_add_f32_e32 v34, 1.0, v34
	v_add_f32_e32 v35, 1.0, v35
	v_rcp_f32_e32 v32, v32
	v_rcp_f32_e32 v33, v33
	v_rcp_f32_e32 v34, v34
	v_rcp_f32_e32 v35, v35
	v_pk_mul_f32 v[20:21], v[20:21], v[32:33]
	v_mul_f32_e32 v32, 0xbfb8aa3b, v16
	v_pk_mul_f32 v[22:23], v[22:23], v[34:35]
	v_mul_f32_e32 v33, 0xbfb8aa3b, v17
	v_mul_f32_e32 v34, 0xbfb8aa3b, v18
	v_mul_f32_e32 v35, 0xbfb8aa3b, v19
	v_exp_f32_e32 v32, v32
	v_exp_f32_e32 v33, v33
	v_exp_f32_e32 v34, v34
	v_exp_f32_e32 v35, v35
	v_add_f32_e32 v32, 1.0, v32
	v_add_f32_e32 v33, 1.0, v33
	v_add_f32_e32 v34, 1.0, v34
	v_add_f32_e32 v35, 1.0, v35
	v_rcp_f32_e32 v32, v32
	v_rcp_f32_e32 v33, v33
	v_rcp_f32_e32 v34, v34
	v_rcp_f32_e32 v35, v35
	v_pk_mul_f32 v[16:17], v[16:17], v[32:33]
	v_pk_mul_f32 v[18:19], v[18:19], v[34:35]
.LBB0_292:
	v_pk_mul_f32 v[22:23], v[30:31], v[22:23]
	v_pk_mul_f32 v[20:21], v[28:29], v[20:21]
	v_pk_mul_f32 v[26:27], v[26:27], v[18:19]
	v_pk_mul_f32 v[18:19], v[24:25], v[16:17]
	v_cvt_pk_bf16_f32 v16, v20, v21
	v_cvt_pk_bf16_f32 v17, v22, v23
	v_add_u32_e32 v22, 0xa0, v155
	v_mov_b64_e32 v[20:21], s[74:75]
	v_mad_i64_i32 v[20:21], s[20:21], v22, s97, v[20:21]
	v_lshl_add_u64 v[20:21], v[140:141], 1, v[20:21]
	s_and_b64 vcc, exec, s[4:5]
	v_cvt_pk_bf16_f32 v18, v18, v19
	v_cvt_pk_bf16_f32 v19, v26, v27
	s_cmp_eq_u32 s34, 4
	s_cbranch_scc1 .Lwt3_6
	global_store_dwordx4 v[20:21], v[16:19], off
	s_branch .Lwj3_6
.Lwt3_6:
	global_store_dwordx4 v[20:21], v[16:19], off sc1
.Lwj3_6:
	s_cbranch_vccnz .LBB0_294
	s_nop 0
	v_mul_f32_e32 v16, 0xbfb8aa3b, v4
	v_mul_f32_e32 v17, 0xbfb8aa3b, v5
	v_mul_f32_e32 v18, 0xbfb8aa3b, v6
	v_mul_f32_e32 v19, 0xbfb8aa3b, v7
	v_exp_f32_e32 v16, v16
	v_exp_f32_e32 v17, v17
	v_exp_f32_e32 v18, v18
	v_exp_f32_e32 v19, v19
	v_add_f32_e32 v16, 1.0, v16
	v_add_f32_e32 v17, 1.0, v17
	v_add_f32_e32 v18, 1.0, v18
	v_add_f32_e32 v19, 1.0, v19
	v_rcp_f32_e32 v16, v16
	v_rcp_f32_e32 v17, v17
	v_rcp_f32_e32 v18, v18
	v_rcp_f32_e32 v19, v19
	v_pk_mul_f32 v[4:5], v[4:5], v[16:17]
	v_mul_f32_e32 v16, 0xbfb8aa3b, v0
	v_pk_mul_f32 v[6:7], v[6:7], v[18:19]
	v_mul_f32_e32 v17, 0xbfb8aa3b, v1
	v_mul_f32_e32 v18, 0xbfb8aa3b, v2
	v_mul_f32_e32 v19, 0xbfb8aa3b, v3
	v_exp_f32_e32 v16, v16
	v_exp_f32_e32 v17, v17
	v_exp_f32_e32 v18, v18
	v_exp_f32_e32 v19, v19
	v_add_f32_e32 v16, 1.0, v16
	v_add_f32_e32 v17, 1.0, v17
	v_add_f32_e32 v18, 1.0, v18
	v_add_f32_e32 v19, 1.0, v19
	v_rcp_f32_e32 v16, v16
	v_rcp_f32_e32 v17, v17
	v_rcp_f32_e32 v18, v18
	v_rcp_f32_e32 v19, v19
	v_pk_mul_f32 v[0:1], v[0:1], v[16:17]
	v_pk_mul_f32 v[2:3], v[2:3], v[18:19]
.LBB0_294:
	v_pk_mul_f32 v[6:7], v[14:15], v[6:7]
	v_pk_mul_f32 v[4:5], v[12:13], v[4:5]
	v_pk_mul_f32 v[10:11], v[10:11], v[2:3]
	v_pk_mul_f32 v[2:3], v[8:9], v[0:1]
	v_cvt_pk_bf16_f32 v0, v4, v5
	v_cvt_pk_bf16_f32 v1, v6, v7
	v_add_u32_e32 v6, 0xb0, v155
	v_mov_b64_e32 v[4:5], s[74:75]
	v_mad_i64_i32 v[4:5], s[4:5], v6, s97, v[4:5]
	v_lshl_add_u64 v[4:5], v[140:141], 1, v[4:5]
	v_cvt_pk_bf16_f32 v2, v2, v3
	v_cvt_pk_bf16_f32 v3, v10, v11
	s_cmp_eq_u32 s34, 4
	s_cbranch_scc1 .Lwt3_7
	global_store_dwordx4 v[4:5], v[0:3], off
	s_branch .Lwj3_7
.Lwt3_7:
	global_store_dwordx4 v[4:5], v[0:3], off sc1
.Lwj3_7:
	s_andn2_b64 vcc, exec, s[0:1]
	s_mov_b64 s[0:1], -1
	s_cbranch_vccnz .LBB0_266
	s_branch .LBB0_330
.LBB0_295:
	v_lshl_add_u32 v155, s4, 8, v150
	s_cmp_gt_i32 s18, 7
	s_mov_b64 s[4:5], -1
	s_cbranch_scc0 .LBB0_277

; __device__ __forceinline__ unsigned cvt_pk_bf16(float lo, float hi) { unsigned r; asm volatile("v_cvt_pk_bf16_f32 %0, %1, %2" : "=v"(r) : "v"(lo), "v"(hi)); return r; }
; __device__ __forceinline__ float silu_f(float v) { return v * __builtin_amdgcn_rcpf(1.0f + __builtin_amdgcn_exp2f(-v * LOG2E_)); }
;     __device__ __forceinline__ void operator()(const f32x4 (&acc)[2][2][4][2], const Unit& u, int wr, int wc, int fr, int fq) const {
;     ...
;         } else {
;             const int col0 = u.pn * BM - 1024 + wc * 32 + 8 * fq;
;             const bool za = u.pn >= 11;
; #pragma unroll
;             for (int ai = 0; ai < 2; ++ai)
; #pragma unroll
;                 for (int m = 0; m < 4; ++m) { bf16_t* rowp = O + (size_t)(row0 + ai * HALF + m * 16) * PO2 + col0;
; #pragma unroll
;                     for (int bj = 0; bj < 2; ++bj) { f32x4 v0 = acc[ai][bj][m][0], v1 = acc[ai][bj][m][1];
;                         if (za) { v0 = (f32x4){silu_f(v0[0]), silu_f(v0[1]), silu_f(v0[2]), silu_f(v0[3])}; v1 = (f32x4){silu_f(v1[0]), silu_f(v1[1]), silu_f(v1[2]), silu_f(v1[3])}; }
;                         u32x4 w; w.x = cvt_pk_bf16(v0[0], v0[1]); w.y = cvt_pk_bf16(v0[2], v0[3]); w.z = cvt_pk_bf16(v1[0], v1[1]); w.w = cvt_pk_bf16(v1[2], v1[3]);
;                         *(u32x4*)(rowp + bj * HALF) = w; } }
;         }
.LBB0_298:
	v_mov_b64_e32 v[140:141], s[74:75]
	v_lshl_add_u32 v172, s18, 8, v153
	v_mad_i64_i32 v[140:141], s[4:5], v155, s97, v[140:141]
	v_lshl_add_u64 v[140:141], v[172:173], 1, v[140:141]
	v_cvt_pk_bf16_f32 v146, v146, v147
	v_cvt_pk_bf16_f32 v147, v142, v143
	v_cvt_pk_bf16_f32 v148, v148, v149
	v_cvt_pk_bf16_f32 v149, v144, v145
	v_cndmask_b32_e64 v142, 0, 1, s[20:21]
	s_cmp_eq_u32 s34, 4
	s_cbranch_scc1 .Lwt3_8
	global_store_dwordx4 v[140:141], v[146:149], off
	s_branch .Lwj3_8
.Lwt3_8:
	global_store_dwordx4 v[140:141], v[146:149], off sc1
.Lwj3_8:
	v_cmp_ne_u32_e64 s[4:5], 1, v142
	s_andn2_b64 vcc, exec, s[20:21]
	v_mov_b32_e32 v145, v115
	v_mov_b32_e32 v144, v114
	v_mov_b32_e32 v149, v113
	v_mov_b32_e32 v148, v112
	v_mov_b32_e32 v143, v119
	v_mov_b32_e32 v142, v118
	v_mov_b32_e32 v147, v117
	v_mov_b32_e32 v146, v116
	s_cbranch_vccnz .LBB0_300
	v_mul_f32_e32 v142, 0xbfb8aa3b, v116
	v_exp_f32_e32 v142, v142
	v_mul_f32_e32 v143, 0xbfb8aa3b, v117
	v_mul_f32_e32 v144, 0xbfb8aa3b, v118
	v_exp_f32_e32 v143, v143
	v_exp_f32_e32 v146, v144
	v_add_f32_e32 v142, 1.0, v142
	v_rcp_f32_e32 v144, v142
	v_add_f32_e32 v142, 1.0, v143
	v_rcp_f32_e32 v145, v142
	v_add_f32_e32 v142, 1.0, v146
	v_mul_f32_e32 v146, 0xbfb8aa3b, v112
	v_exp_f32_e32 v146, v146
	v_mul_f32_e32 v147, 0xbfb8aa3b, v114
	v_mul_f32_e32 v143, 0xbfb8aa3b, v119
	v_exp_f32_e32 v147, v147
	v_add_f32_e32 v146, 1.0, v146
	v_rcp_f32_e32 v148, v146
	v_mul_f32_e32 v146, 0xbfb8aa3b, v113
	v_mul_f32_e32 v149, 0xbfb8aa3b, v115
	v_exp_f32_e32 v143, v143
	v_exp_f32_e32 v146, v146
	v_exp_f32_e32 v149, v149
	v_add_f32_e32 v147, 1.0, v147
	v_add_f32_e32 v143, 1.0, v143
	v_add_f32_e32 v146, 1.0, v146
	v_rcp_f32_e32 v156, v147
	v_add_f32_e32 v147, 1.0, v149
	v_rcp_f32_e32 v142, v142
	v_rcp_f32_e32 v143, v143
	v_rcp_f32_e32 v157, v147
	v_rcp_f32_e32 v149, v146
	v_pk_mul_f32 v[146:147], v[116:117], v[144:145]
	v_pk_mul_f32 v[142:143], v[118:119], v[142:143]
	v_pk_mul_f32 v[144:145], v[114:115], v[156:157]
	v_pk_mul_f32 v[148:149], v[112:113], v[148:149]
.LBB0_300:
	v_cvt_pk_bf16_f32 v146, v146, v147
	v_cvt_pk_bf16_f32 v147, v142, v143
	s_nop 0
	v_cvt_pk_bf16_f32 v148, v148, v149
	v_cvt_pk_bf16_f32 v149, v144, v145
	s_cmp_eq_u32 s34, 4
	s_cbranch_scc1 .Lwt3_9
	global_store_dwordx4 v[140:141], v[146:149], off offset:256
	s_branch .Lwj3_9
.Lwt3_9:
	global_store_dwordx4 v[140:141], v[146:149], off offset:256 sc1
.Lwj3_9:
	s_and_b64 vcc, exec, s[4:5]
	v_mov_b32_e32 v145, v107
	v_mov_b32_e32 v144, v106
	v_mov_b32_e32 v149, v105
	v_mov_b32_e32 v148, v104
	v_mov_b32_e32 v143, v111
	v_mov_b32_e32 v142, v110
	v_mov_b32_e32 v147, v109
	v_mov_b32_e32 v146, v108
	s_cbranch_vccnz .LBB0_302
	v_mul_f32_e32 v144, 0xbfb8aa3b, v104
	v_exp_f32_e32 v144, v144
	v_mul_f32_e32 v140, 0xbfb8aa3b, v108
	v_mul_f32_e32 v141, 0xbfb8aa3b, v109
	v_mul_f32_e32 v142, 0xbfb8aa3b, v110
	v_add_f32_e32 v144, 1.0, v144
	v_mul_f32_e32 v143, 0xbfb8aa3b, v111
	v_rcp_f32_e32 v148, v144
	v_mul_f32_e32 v144, 0xbfb8aa3b, v105
	v_mul_f32_e32 v145, 0xbfb8aa3b, v106
	v_mul_f32_e32 v146, 0xbfb8aa3b, v107
	v_exp_f32_e32 v140, v140
	v_exp_f32_e32 v141, v141
	v_exp_f32_e32 v142, v142
	v_exp_f32_e32 v143, v143
	v_exp_f32_e32 v144, v144
	v_exp_f32_e32 v145, v145
	v_exp_f32_e32 v146, v146
	v_add_f32_e32 v140, 1.0, v140
	v_add_f32_e32 v141, 1.0, v141
	v_add_f32_e32 v142, 1.0, v142
	v_add_f32_e32 v143, 1.0, v143
	v_add_f32_e32 v147, 1.0, v144
	v_add_f32_e32 v144, 1.0, v145
	v_add_f32_e32 v145, 1.0, v146
	v_rcp_f32_e32 v140, v140
	v_rcp_f32_e32 v141, v141
	v_rcp_f32_e32 v142, v142
	v_rcp_f32_e32 v143, v143
	v_rcp_f32_e32 v144, v144
	v_rcp_f32_e32 v145, v145
	v_rcp_f32_e32 v149, v147
	v_pk_mul_f32 v[142:143], v[110:111], v[142:143]
	v_pk_mul_f32 v[146:147], v[108:109], v[140:141]
	v_pk_mul_f32 v[144:145], v[106:107], v[144:145]
	v_pk_mul_f32 v[148:149], v[104:105], v[148:149]
.LBB0_302:
	v_or_b32_e32 v156, 16, v155
	v_mov_b64_e32 v[140:141], s[74:75]
	v_mad_i64_i32 v[140:141], s[20:21], v156, s97, v[140:141]
	v_lshl_add_u64 v[140:141], v[172:173], 1, v[140:141]
	v_cvt_pk_bf16_f32 v146, v146, v147
	v_cvt_pk_bf16_f32 v147, v142, v143
	v_cvt_pk_bf16_f32 v148, v148, v149
	v_cvt_pk_bf16_f32 v149, v144, v145
	s_cmp_eq_u32 s34, 4
	s_cbranch_scc1 .Lwt3_10
	global_store_dwordx4 v[140:141], v[146:149], off
	s_branch .Lwj3_10

; __device__ __forceinline__ unsigned cvt_pk_bf16(float lo, float hi) { unsigned r; asm volatile("v_cvt_pk_bf16_f32 %0, %1, %2" : "=v"(r) : "v"(lo), "v"(hi)); return r; }
; __device__ __forceinline__ float silu_f(float v) { return v * __builtin_amdgcn_rcpf(1.0f + __builtin_amdgcn_exp2f(-v * LOG2E_)); }
;     __device__ __forceinline__ void operator()(const f32x4 (&acc)[2][2][4][2], const Unit& u, int wr, int wc, int fr, int fq) const {
;     ...
;                     for (int bj = 0; bj < 2; ++bj) { f32x4 v0 = acc[ai][bj][m][0], v1 = acc[ai][bj][m][1];
;                         if (za) { v0 = (f32x4){silu_f(v0[0]), silu_f(v0[1]), silu_f(v0[2]), silu_f(v0[3])}; v1 = (f32x4){silu_f(v1[0]), silu_f(v1[1]), silu_f(v1[2]), silu_f(v1[3])}; }
;                         u32x4 w; w.x = cvt_pk_bf16(v0[0], v0[1]); w.y = cvt_pk_bf16(v0[2], v0[3]); w.z = cvt_pk_bf16(v1[0], v1[1]); w.w = cvt_pk_bf16(v1[2], v1[3]);
;                         *(u32x4*)(rowp + bj * HALF) = w; } }
.Lwj3_10:
	s_and_b64 vcc, exec, s[4:5]
	v_mov_b32_e32 v145, v99
	v_mov_b32_e32 v144, v98
	v_mov_b32_e32 v149, v97
	v_mov_b32_e32 v148, v96
	v_mov_b32_e32 v143, v103
	v_mov_b32_e32 v142, v102
	v_mov_b32_e32 v147, v101
	v_mov_b32_e32 v146, v100
	s_cbranch_vccnz .LBB0_304
	v_mul_f32_e32 v142, 0xbfb8aa3b, v100
	v_exp_f32_e32 v142, v142
	v_mul_f32_e32 v143, 0xbfb8aa3b, v101
	v_mul_f32_e32 v144, 0xbfb8aa3b, v102
	v_exp_f32_e32 v143, v143
	v_exp_f32_e32 v146, v144
	v_add_f32_e32 v142, 1.0, v142
	v_rcp_f32_e32 v144, v142
	v_add_f32_e32 v142, 1.0, v143
	v_rcp_f32_e32 v145, v142
	v_add_f32_e32 v142, 1.0, v146
	v_mul_f32_e32 v146, 0xbfb8aa3b, v96
	v_exp_f32_e32 v146, v146
	v_mul_f32_e32 v147, 0xbfb8aa3b, v98
	v_mul_f32_e32 v143, 0xbfb8aa3b, v103
	v_exp_f32_e32 v147, v147
	v_add_f32_e32 v146, 1.0, v146
	v_rcp_f32_e32 v148, v146
	v_mul_f32_e32 v146, 0xbfb8aa3b, v97
	v_mul_f32_e32 v149, 0xbfb8aa3b, v99
	v_exp_f32_e32 v143, v143
	v_exp_f32_e32 v146, v146
	v_exp_f32_e32 v149, v149
	v_add_f32_e32 v147, 1.0, v147
	v_add_f32_e32 v143, 1.0, v143
	v_add_f32_e32 v146, 1.0, v146
	v_rcp_f32_e32 v156, v147
	v_add_f32_e32 v147, 1.0, v149
	v_rcp_f32_e32 v142, v142
	v_rcp_f32_e32 v143, v143
	v_rcp_f32_e32 v157, v147
	v_rcp_f32_e32 v149, v146
	v_pk_mul_f32 v[146:147], v[100:101], v[144:145]
	v_pk_mul_f32 v[142:143], v[102:103], v[142:143]
	v_pk_mul_f32 v[144:145], v[98:99], v[156:157]
	v_pk_mul_f32 v[148:149], v[96:97], v[148:149]

; __device__ __forceinline__ unsigned cvt_pk_bf16(float lo, float hi) { unsigned r; asm volatile("v_cvt_pk_bf16_f32 %0, %1, %2" : "=v"(r) : "v"(lo), "v"(hi)); return r; }
; __device__ __forceinline__ float silu_f(float v) { return v * __builtin_amdgcn_rcpf(1.0f + __builtin_amdgcn_exp2f(-v * LOG2E_)); }
;     __device__ __forceinline__ void operator()(const f32x4 (&acc)[2][2][4][2], const Unit& u, int wr, int wc, int fr, int fq) const {
;     ...
;                 for (int m = 0; m < 4; ++m) { bf16_t* rowp = O + (size_t)(row0 + ai * HALF + m * 16) * PO2 + col0;
; #pragma unroll
;                     for (int bj = 0; bj < 2; ++bj) { f32x4 v0 = acc[ai][bj][m][0], v1 = acc[ai][bj][m][1];
;                         if (za) { v0 = (f32x4){silu_f(v0[0]), silu_f(v0[1]), silu_f(v0[2]), silu_f(v0[3])}; v1 = (f32x4){silu_f(v1[0]), silu_f(v1[1]), silu_f(v1[2]), silu_f(v1[3])}; }
;                         u32x4 w; w.x = cvt_pk_bf16(v0[0], v0[1]); w.y = cvt_pk_bf16(v0[2], v0[3]); w.z = cvt_pk_bf16(v1[0], v1[1]); w.w = cvt_pk_bf16(v1[2], v1[3]);
;                         *(u32x4*)(rowp + bj * HALF) = w; } }
.Lwj3_11:
	s_and_b64 vcc, exec, s[4:5]
	v_mov_b32_e32 v145, v91
	v_mov_b32_e32 v144, v90
	v_mov_b32_e32 v149, v89
	v_mov_b32_e32 v148, v88
	v_mov_b32_e32 v143, v95
	v_mov_b32_e32 v142, v94
	v_mov_b32_e32 v147, v93
	v_mov_b32_e32 v146, v92
	s_cbranch_vccnz .LBB0_306
	v_mul_f32_e32 v144, 0xbfb8aa3b, v88
	v_exp_f32_e32 v144, v144
	v_mul_f32_e32 v140, 0xbfb8aa3b, v92
	v_mul_f32_e32 v141, 0xbfb8aa3b, v93
	v_mul_f32_e32 v142, 0xbfb8aa3b, v94
	v_add_f32_e32 v144, 1.0, v144
	v_mul_f32_e32 v143, 0xbfb8aa3b, v95
	v_rcp_f32_e32 v148, v144
	v_mul_f32_e32 v144, 0xbfb8aa3b, v89
	v_mul_f32_e32 v145, 0xbfb8aa3b, v90
	v_mul_f32_e32 v146, 0xbfb8aa3b, v91
	v_exp_f32_e32 v140, v140
	v_exp_f32_e32 v141, v141
	v_exp_f32_e32 v142, v142
	v_exp_f32_e32 v143, v143
	v_exp_f32_e32 v144, v144
	v_exp_f32_e32 v145, v145
	v_exp_f32_e32 v146, v146
	v_add_f32_e32 v140, 1.0, v140
	v_add_f32_e32 v141, 1.0, v141
	v_add_f32_e32 v142, 1.0, v142
	v_add_f32_e32 v143, 1.0, v143
	v_add_f32_e32 v147, 1.0, v144
	v_add_f32_e32 v144, 1.0, v145
	v_add_f32_e32 v145, 1.0, v146
	v_rcp_f32_e32 v140, v140
	v_rcp_f32_e32 v141, v141
	v_rcp_f32_e32 v142, v142
	v_rcp_f32_e32 v143, v143
	v_rcp_f32_e32 v144, v144
	v_rcp_f32_e32 v145, v145
	v_rcp_f32_e32 v149, v147
	v_pk_mul_f32 v[142:143], v[94:95], v[142:143]
	v_pk_mul_f32 v[146:147], v[92:93], v[140:141]
	v_pk_mul_f32 v[144:145], v[90:91], v[144:145]
	v_pk_mul_f32 v[148:149], v[88:89], v[148:149]
.LBB0_306:
	v_or_b32_e32 v156, 32, v155
	v_mov_b64_e32 v[140:141], s[74:75]
	v_mad_i64_i32 v[140:141], s[20:21], v156, s97, v[140:141]
	v_lshl_add_u64 v[140:141], v[172:173], 1, v[140:141]
	v_cvt_pk_bf16_f32 v146, v146, v147
	v_cvt_pk_bf16_f32 v147, v142, v143
	v_cvt_pk_bf16_f32 v148, v148, v149
	v_cvt_pk_bf16_f32 v149, v144, v145
	s_cmp_eq_u32 s34, 4
	s_cbranch_scc1 .Lwt3_12
	global_store_dwordx4 v[140:141], v[146:149], off
	s_branch .Lwj3_12

; __device__ __forceinline__ unsigned cvt_pk_bf16(float lo, float hi) { unsigned r; asm volatile("v_cvt_pk_bf16_f32 %0, %1, %2" : "=v"(r) : "v"(lo), "v"(hi)); return r; }
; __device__ __forceinline__ float silu_f(float v) { return v * __builtin_amdgcn_rcpf(1.0f + __builtin_amdgcn_exp2f(-v * LOG2E_)); }
;     __device__ __forceinline__ void operator()(const f32x4 (&acc)[2][2][4][2], const Unit& u, int wr, int wc, int fr, int fq) const {
;     ...
;                     for (int bj = 0; bj < 2; ++bj) { f32x4 v0 = acc[ai][bj][m][0], v1 = acc[ai][bj][m][1];
;                         if (za) { v0 = (f32x4){silu_f(v0[0]), silu_f(v0[1]), silu_f(v0[2]), silu_f(v0[3])}; v1 = (f32x4){silu_f(v1[0]), silu_f(v1[1]), silu_f(v1[2]), silu_f(v1[3])}; }
;                         u32x4 w; w.x = cvt_pk_bf16(v0[0], v0[1]); w.y = cvt_pk_bf16(v0[2], v0[3]); w.z = cvt_pk_bf16(v1[0], v1[1]); w.w = cvt_pk_bf16(v1[2], v1[3]);
;                         *(u32x4*)(rowp + bj * HALF) = w; } }
.Lwj3_12:
	s_and_b64 vcc, exec, s[4:5]
	v_mov_b32_e32 v145, v83
	v_mov_b32_e32 v144, v82
	v_mov_b32_e32 v149, v81
	v_mov_b32_e32 v148, v80
	v_mov_b32_e32 v143, v87
	v_mov_b32_e32 v142, v86
	v_mov_b32_e32 v147, v85
	v_mov_b32_e32 v146, v84
	s_cbranch_vccnz .LBB0_308
	v_mul_f32_e32 v142, 0xbfb8aa3b, v84
	v_exp_f32_e32 v142, v142
	v_mul_f32_e32 v143, 0xbfb8aa3b, v85
	v_mul_f32_e32 v144, 0xbfb8aa3b, v86
	v_exp_f32_e32 v143, v143
	v_exp_f32_e32 v146, v144
	v_add_f32_e32 v142, 1.0, v142
	v_rcp_f32_e32 v144, v142
	v_add_f32_e32 v142, 1.0, v143
	v_rcp_f32_e32 v145, v142
	v_add_f32_e32 v142, 1.0, v146
	v_mul_f32_e32 v146, 0xbfb8aa3b, v80
	v_exp_f32_e32 v146, v146
	v_mul_f32_e32 v147, 0xbfb8aa3b, v82
	v_mul_f32_e32 v143, 0xbfb8aa3b, v87
	v_exp_f32_e32 v147, v147
	v_add_f32_e32 v146, 1.0, v146
	v_rcp_f32_e32 v148, v146
	v_mul_f32_e32 v146, 0xbfb8aa3b, v81
	v_mul_f32_e32 v149, 0xbfb8aa3b, v83
	v_exp_f32_e32 v143, v143
	v_exp_f32_e32 v146, v146
	v_exp_f32_e32 v149, v149
	v_add_f32_e32 v147, 1.0, v147
	v_add_f32_e32 v143, 1.0, v143
	v_add_f32_e32 v146, 1.0, v146
	v_rcp_f32_e32 v156, v147
	v_add_f32_e32 v147, 1.0, v149
	v_rcp_f32_e32 v142, v142
	v_rcp_f32_e32 v143, v143
	v_rcp_f32_e32 v157, v147
	v_rcp_f32_e32 v149, v146
	v_pk_mul_f32 v[146:147], v[84:85], v[144:145]
	v_pk_mul_f32 v[142:143], v[86:87], v[142:143]
	v_pk_mul_f32 v[144:145], v[82:83], v[156:157]
	v_pk_mul_f32 v[148:149], v[80:81], v[148:149]

; __device__ __forceinline__ unsigned cvt_pk_bf16(float lo, float hi) { unsigned r; asm volatile("v_cvt_pk_bf16_f32 %0, %1, %2" : "=v"(r) : "v"(lo), "v"(hi)); return r; }
; __device__ __forceinline__ float silu_f(float v) { return v * __builtin_amdgcn_rcpf(1.0f + __builtin_amdgcn_exp2f(-v * LOG2E_)); }
;     __device__ __forceinline__ void operator()(const f32x4 (&acc)[2][2][4][2], const Unit& u, int wr, int wc, int fr, int fq) const {
;     ...
;                 for (int m = 0; m < 4; ++m) { bf16_t* rowp = O + (size_t)(row0 + ai * HALF + m * 16) * PO2 + col0;
; #pragma unroll
;                     for (int bj = 0; bj < 2; ++bj) { f32x4 v0 = acc[ai][bj][m][0], v1 = acc[ai][bj][m][1];
;                         if (za) { v0 = (f32x4){silu_f(v0[0]), silu_f(v0[1]), silu_f(v0[2]), silu_f(v0[3])}; v1 = (f32x4){silu_f(v1[0]), silu_f(v1[1]), silu_f(v1[2]), silu_f(v1[3])}; }
;                         u32x4 w; w.x = cvt_pk_bf16(v0[0], v0[1]); w.y = cvt_pk_bf16(v0[2], v0[3]); w.z = cvt_pk_bf16(v1[0], v1[1]); w.w = cvt_pk_bf16(v1[2], v1[3]);
;                         *(u32x4*)(rowp + bj * HALF) = w; } }
.Lwj3_13:
	s_and_b64 vcc, exec, s[4:5]
	v_mov_b32_e32 v145, v75
	v_mov_b32_e32 v144, v74
	v_mov_b32_e32 v149, v73
	v_mov_b32_e32 v148, v72
	v_mov_b32_e32 v143, v79
	v_mov_b32_e32 v142, v78
	v_mov_b32_e32 v147, v77
	v_mov_b32_e32 v146, v76
	s_cbranch_vccnz .LBB0_310
	v_mul_f32_e32 v144, 0xbfb8aa3b, v72
	v_exp_f32_e32 v144, v144
	v_mul_f32_e32 v140, 0xbfb8aa3b, v76
	v_mul_f32_e32 v141, 0xbfb8aa3b, v77
	v_mul_f32_e32 v142, 0xbfb8aa3b, v78
	v_add_f32_e32 v144, 1.0, v144
	v_mul_f32_e32 v143, 0xbfb8aa3b, v79
	v_rcp_f32_e32 v148, v144
	v_mul_f32_e32 v144, 0xbfb8aa3b, v73
	v_mul_f32_e32 v145, 0xbfb8aa3b, v74
	v_mul_f32_e32 v146, 0xbfb8aa3b, v75
	v_exp_f32_e32 v140, v140
	v_exp_f32_e32 v141, v141
	v_exp_f32_e32 v142, v142
	v_exp_f32_e32 v143, v143
	v_exp_f32_e32 v144, v144
	v_exp_f32_e32 v145, v145
	v_exp_f32_e32 v146, v146
	v_add_f32_e32 v140, 1.0, v140
	v_add_f32_e32 v141, 1.0, v141
	v_add_f32_e32 v142, 1.0, v142
	v_add_f32_e32 v143, 1.0, v143
	v_add_f32_e32 v147, 1.0, v144
	v_add_f32_e32 v144, 1.0, v145
	v_add_f32_e32 v145, 1.0, v146
	v_rcp_f32_e32 v140, v140
	v_rcp_f32_e32 v141, v141
	v_rcp_f32_e32 v142, v142
	v_rcp_f32_e32 v143, v143
	v_rcp_f32_e32 v144, v144
	v_rcp_f32_e32 v145, v145
	v_rcp_f32_e32 v149, v147
	v_pk_mul_f32 v[142:143], v[78:79], v[142:143]
	v_pk_mul_f32 v[146:147], v[76:77], v[140:141]
	v_pk_mul_f32 v[144:145], v[74:75], v[144:145]
	v_pk_mul_f32 v[148:149], v[72:73], v[148:149]
.LBB0_310:
	v_or_b32_e32 v156, 48, v155
	v_mov_b64_e32 v[140:141], s[74:75]
	v_mad_i64_i32 v[140:141], s[20:21], v156, s97, v[140:141]
	v_lshl_add_u64 v[140:141], v[172:173], 1, v[140:141]
	v_cvt_pk_bf16_f32 v146, v146, v147
	v_cvt_pk_bf16_f32 v147, v142, v143
	v_cvt_pk_bf16_f32 v148, v148, v149
	v_cvt_pk_bf16_f32 v149, v144, v145
	s_cmp_eq_u32 s34, 4
	s_cbranch_scc1 .Lwt3_14
	global_store_dwordx4 v[140:141], v[146:149], off
	s_branch .Lwj3_14

; __device__ __forceinline__ unsigned cvt_pk_bf16(float lo, float hi) { unsigned r; asm volatile("v_cvt_pk_bf16_f32 %0, %1, %2" : "=v"(r) : "v"(lo), "v"(hi)); return r; }
; __device__ __forceinline__ float silu_f(float v) { return v * __builtin_amdgcn_rcpf(1.0f + __builtin_amdgcn_exp2f(-v * LOG2E_)); }
;     __device__ __forceinline__ void operator()(const f32x4 (&acc)[2][2][4][2], const Unit& u, int wr, int wc, int fr, int fq) const {
;     ...
;                     for (int bj = 0; bj < 2; ++bj) { f32x4 v0 = acc[ai][bj][m][0], v1 = acc[ai][bj][m][1];
;                         if (za) { v0 = (f32x4){silu_f(v0[0]), silu_f(v0[1]), silu_f(v0[2]), silu_f(v0[3])}; v1 = (f32x4){silu_f(v1[0]), silu_f(v1[1]), silu_f(v1[2]), silu_f(v1[3])}; }
;                         u32x4 w; w.x = cvt_pk_bf16(v0[0], v0[1]); w.y = cvt_pk_bf16(v0[2], v0[3]); w.z = cvt_pk_bf16(v1[0], v1[1]); w.w = cvt_pk_bf16(v1[2], v1[3]);
;                         *(u32x4*)(rowp + bj * HALF) = w; } }
.Lwj3_14:
	s_and_b64 vcc, exec, s[4:5]
	v_mov_b32_e32 v145, v67
	v_mov_b32_e32 v144, v66
	v_mov_b32_e32 v149, v65
	v_mov_b32_e32 v148, v64
	v_mov_b32_e32 v143, v71
	v_mov_b32_e32 v142, v70
	v_mov_b32_e32 v147, v69
	v_mov_b32_e32 v146, v68
	s_cbranch_vccnz .LBB0_312
	v_mul_f32_e32 v142, 0xbfb8aa3b, v68
	v_exp_f32_e32 v142, v142
	v_mul_f32_e32 v143, 0xbfb8aa3b, v69
	v_mul_f32_e32 v144, 0xbfb8aa3b, v70
	v_exp_f32_e32 v143, v143
	v_exp_f32_e32 v146, v144
	v_add_f32_e32 v142, 1.0, v142
	v_rcp_f32_e32 v144, v142
	v_add_f32_e32 v142, 1.0, v143
	v_rcp_f32_e32 v145, v142
	v_add_f32_e32 v142, 1.0, v146
	v_mul_f32_e32 v146, 0xbfb8aa3b, v64
	v_exp_f32_e32 v146, v146
	v_mul_f32_e32 v147, 0xbfb8aa3b, v66
	v_mul_f32_e32 v143, 0xbfb8aa3b, v71
	v_exp_f32_e32 v147, v147
	v_add_f32_e32 v146, 1.0, v146
	v_rcp_f32_e32 v148, v146
	v_mul_f32_e32 v146, 0xbfb8aa3b, v65
	v_mul_f32_e32 v149, 0xbfb8aa3b, v67
	v_exp_f32_e32 v143, v143
	v_exp_f32_e32 v146, v146
	v_exp_f32_e32 v149, v149
	v_add_f32_e32 v147, 1.0, v147
	v_add_f32_e32 v143, 1.0, v143
	v_add_f32_e32 v146, 1.0, v146
	v_rcp_f32_e32 v156, v147
	v_add_f32_e32 v147, 1.0, v149
	v_rcp_f32_e32 v142, v142
	v_rcp_f32_e32 v143, v143
	v_rcp_f32_e32 v157, v147
	v_rcp_f32_e32 v149, v146
	v_pk_mul_f32 v[146:147], v[68:69], v[144:145]
	v_pk_mul_f32 v[142:143], v[70:71], v[142:143]
	v_pk_mul_f32 v[144:145], v[66:67], v[156:157]
	v_pk_mul_f32 v[148:149], v[64:65], v[148:149]

; __device__ __forceinline__ unsigned cvt_pk_bf16(float lo, float hi) { unsigned r; asm volatile("v_cvt_pk_bf16_f32 %0, %1, %2" : "=v"(r) : "v"(lo), "v"(hi)); return r; }
; __device__ __forceinline__ float silu_f(float v) { return v * __builtin_amdgcn_rcpf(1.0f + __builtin_amdgcn_exp2f(-v * LOG2E_)); }
;     __device__ __forceinline__ void operator()(const f32x4 (&acc)[2][2][4][2], const Unit& u, int wr, int wc, int fr, int fq) const {
;     ...
;                 for (int m = 0; m < 4; ++m) { bf16_t* rowp = O + (size_t)(row0 + ai * HALF + m * 16) * PO2 + col0;
; #pragma unroll
;                     for (int bj = 0; bj < 2; ++bj) { f32x4 v0 = acc[ai][bj][m][0], v1 = acc[ai][bj][m][1];
;                         if (za) { v0 = (f32x4){silu_f(v0[0]), silu_f(v0[1]), silu_f(v0[2]), silu_f(v0[3])}; v1 = (f32x4){silu_f(v1[0]), silu_f(v1[1]), silu_f(v1[2]), silu_f(v1[3])}; }
;                         u32x4 w; w.x = cvt_pk_bf16(v0[0], v0[1]); w.y = cvt_pk_bf16(v0[2], v0[3]); w.z = cvt_pk_bf16(v1[0], v1[1]); w.w = cvt_pk_bf16(v1[2], v1[3]);
;                         *(u32x4*)(rowp + bj * HALF) = w; } }
.Lwj3_15:
	s_and_b64 vcc, exec, s[4:5]
	v_mov_b32_e32 v145, v59
	v_mov_b32_e32 v144, v58
	v_mov_b32_e32 v149, v57
	v_mov_b32_e32 v148, v56
	v_mov_b32_e32 v143, v63
	v_mov_b32_e32 v142, v62
	v_mov_b32_e32 v147, v61
	v_mov_b32_e32 v146, v60
	s_cbranch_vccnz .LBB0_314
	v_mul_f32_e32 v144, 0xbfb8aa3b, v56
	v_exp_f32_e32 v144, v144
	v_mul_f32_e32 v140, 0xbfb8aa3b, v60
	v_mul_f32_e32 v141, 0xbfb8aa3b, v61
	v_mul_f32_e32 v142, 0xbfb8aa3b, v62
	v_add_f32_e32 v144, 1.0, v144
	v_mul_f32_e32 v143, 0xbfb8aa3b, v63
	v_rcp_f32_e32 v148, v144
	v_mul_f32_e32 v144, 0xbfb8aa3b, v57
	v_mul_f32_e32 v145, 0xbfb8aa3b, v58
	v_mul_f32_e32 v146, 0xbfb8aa3b, v59
	v_exp_f32_e32 v140, v140
	v_exp_f32_e32 v141, v141
	v_exp_f32_e32 v142, v142
	v_exp_f32_e32 v143, v143
	v_exp_f32_e32 v144, v144
	v_exp_f32_e32 v145, v145
	v_exp_f32_e32 v146, v146
	v_add_f32_e32 v140, 1.0, v140
	v_add_f32_e32 v141, 1.0, v141
	v_add_f32_e32 v142, 1.0, v142
	v_add_f32_e32 v143, 1.0, v143
	v_add_f32_e32 v147, 1.0, v144
	v_add_f32_e32 v144, 1.0, v145
	v_add_f32_e32 v145, 1.0, v146
	v_rcp_f32_e32 v140, v140
	v_rcp_f32_e32 v141, v141
	v_rcp_f32_e32 v142, v142
	v_rcp_f32_e32 v143, v143
	v_rcp_f32_e32 v144, v144
	v_rcp_f32_e32 v145, v145
	v_rcp_f32_e32 v149, v147
	v_pk_mul_f32 v[142:143], v[62:63], v[142:143]
	v_pk_mul_f32 v[146:147], v[60:61], v[140:141]
	v_pk_mul_f32 v[144:145], v[58:59], v[144:145]
	v_pk_mul_f32 v[148:149], v[56:57], v[148:149]
.LBB0_314:
	v_add_u32_e32 v156, 0x80, v155
	v_mov_b64_e32 v[140:141], s[74:75]
	v_mad_i64_i32 v[140:141], s[20:21], v156, s97, v[140:141]
	v_lshl_add_u64 v[140:141], v[172:173], 1, v[140:141]
	v_cvt_pk_bf16_f32 v146, v146, v147
	v_cvt_pk_bf16_f32 v147, v142, v143
	v_cvt_pk_bf16_f32 v148, v148, v149
	v_cvt_pk_bf16_f32 v149, v144, v145
	s_cmp_eq_u32 s34, 4
	s_cbranch_scc1 .Lwt3_16
	global_store_dwordx4 v[140:141], v[146:149], off
	s_branch .Lwj3_16

; __device__ __forceinline__ unsigned cvt_pk_bf16(float lo, float hi) { unsigned r; asm volatile("v_cvt_pk_bf16_f32 %0, %1, %2" : "=v"(r) : "v"(lo), "v"(hi)); return r; }
; __device__ __forceinline__ float silu_f(float v) { return v * __builtin_amdgcn_rcpf(1.0f + __builtin_amdgcn_exp2f(-v * LOG2E_)); }
;     __device__ __forceinline__ void operator()(const f32x4 (&acc)[2][2][4][2], const Unit& u, int wr, int wc, int fr, int fq) const {
;     ...
;                     for (int bj = 0; bj < 2; ++bj) { f32x4 v0 = acc[ai][bj][m][0], v1 = acc[ai][bj][m][1];
;                         if (za) { v0 = (f32x4){silu_f(v0[0]), silu_f(v0[1]), silu_f(v0[2]), silu_f(v0[3])}; v1 = (f32x4){silu_f(v1[0]), silu_f(v1[1]), silu_f(v1[2]), silu_f(v1[3])}; }
;                         u32x4 w; w.x = cvt_pk_bf16(v0[0], v0[1]); w.y = cvt_pk_bf16(v0[2], v0[3]); w.z = cvt_pk_bf16(v1[0], v1[1]); w.w = cvt_pk_bf16(v1[2], v1[3]);
;                         *(u32x4*)(rowp + bj * HALF) = w; } }
.Lwj3_16:
	s_and_b64 vcc, exec, s[4:5]
	v_mov_b32_e32 v145, v51
	v_mov_b32_e32 v144, v50
	v_mov_b32_e32 v149, v49
	v_mov_b32_e32 v148, v48
	v_mov_b32_e32 v143, v55
	v_mov_b32_e32 v142, v54
	v_mov_b32_e32 v147, v53
	v_mov_b32_e32 v146, v52
	s_cbranch_vccnz .LBB0_316
	v_mul_f32_e32 v142, 0xbfb8aa3b, v52
	v_exp_f32_e32 v142, v142
	v_mul_f32_e32 v143, 0xbfb8aa3b, v53
	v_mul_f32_e32 v144, 0xbfb8aa3b, v54
	v_exp_f32_e32 v143, v143
	v_exp_f32_e32 v146, v144
	v_add_f32_e32 v142, 1.0, v142
	v_rcp_f32_e32 v144, v142
	v_add_f32_e32 v142, 1.0, v143
	v_rcp_f32_e32 v145, v142
	v_add_f32_e32 v142, 1.0, v146
	v_mul_f32_e32 v146, 0xbfb8aa3b, v48
	v_exp_f32_e32 v146, v146
	v_mul_f32_e32 v147, 0xbfb8aa3b, v50
	v_mul_f32_e32 v143, 0xbfb8aa3b, v55
	v_exp_f32_e32 v147, v147
	v_add_f32_e32 v146, 1.0, v146
	v_rcp_f32_e32 v148, v146
	v_mul_f32_e32 v146, 0xbfb8aa3b, v49
	v_mul_f32_e32 v149, 0xbfb8aa3b, v51
	v_exp_f32_e32 v143, v143
	v_exp_f32_e32 v146, v146
	v_exp_f32_e32 v149, v149
	v_add_f32_e32 v147, 1.0, v147
	v_add_f32_e32 v143, 1.0, v143
	v_add_f32_e32 v146, 1.0, v146
	v_rcp_f32_e32 v156, v147
	v_add_f32_e32 v147, 1.0, v149
	v_rcp_f32_e32 v142, v142
	v_rcp_f32_e32 v143, v143
	v_rcp_f32_e32 v157, v147
	v_rcp_f32_e32 v149, v146
	v_pk_mul_f32 v[146:147], v[52:53], v[144:145]
	v_pk_mul_f32 v[142:143], v[54:55], v[142:143]
	v_pk_mul_f32 v[144:145], v[50:51], v[156:157]
	v_pk_mul_f32 v[148:149], v[48:49], v[148:149]

; __device__ __forceinline__ unsigned cvt_pk_bf16(float lo, float hi) { unsigned r; asm volatile("v_cvt_pk_bf16_f32 %0, %1, %2" : "=v"(r) : "v"(lo), "v"(hi)); return r; }
; __device__ __forceinline__ float silu_f(float v) { return v * __builtin_amdgcn_rcpf(1.0f + __builtin_amdgcn_exp2f(-v * LOG2E_)); }
;     __device__ __forceinline__ void operator()(const f32x4 (&acc)[2][2][4][2], const Unit& u, int wr, int wc, int fr, int fq) const {
;     ...
;                 for (int m = 0; m < 4; ++m) { bf16_t* rowp = O + (size_t)(row0 + ai * HALF + m * 16) * PO2 + col0;
; #pragma unroll
;                     for (int bj = 0; bj < 2; ++bj) { f32x4 v0 = acc[ai][bj][m][0], v1 = acc[ai][bj][m][1];
;                         if (za) { v0 = (f32x4){silu_f(v0[0]), silu_f(v0[1]), silu_f(v0[2]), silu_f(v0[3])}; v1 = (f32x4){silu_f(v1[0]), silu_f(v1[1]), silu_f(v1[2]), silu_f(v1[3])}; }
;                         u32x4 w; w.x = cvt_pk_bf16(v0[0], v0[1]); w.y = cvt_pk_bf16(v0[2], v0[3]); w.z = cvt_pk_bf16(v1[0], v1[1]); w.w = cvt_pk_bf16(v1[2], v1[3]);
;                         *(u32x4*)(rowp + bj * HALF) = w; } }
.Lwj3_17:
	s_and_b64 vcc, exec, s[4:5]
	v_mov_b32_e32 v145, v43
	v_mov_b32_e32 v144, v42
	v_mov_b32_e32 v149, v41
	v_mov_b32_e32 v148, v40
	v_mov_b32_e32 v143, v47
	v_mov_b32_e32 v142, v46
	v_mov_b32_e32 v147, v45
	v_mov_b32_e32 v146, v44
	s_cbranch_vccnz .LBB0_318
	v_mul_f32_e32 v144, 0xbfb8aa3b, v40
	v_exp_f32_e32 v144, v144
	v_mul_f32_e32 v140, 0xbfb8aa3b, v44
	v_mul_f32_e32 v141, 0xbfb8aa3b, v45
	v_mul_f32_e32 v142, 0xbfb8aa3b, v46
	v_add_f32_e32 v144, 1.0, v144
	v_mul_f32_e32 v143, 0xbfb8aa3b, v47
	v_rcp_f32_e32 v148, v144
	v_mul_f32_e32 v144, 0xbfb8aa3b, v41
	v_mul_f32_e32 v145, 0xbfb8aa3b, v42
	v_mul_f32_e32 v146, 0xbfb8aa3b, v43
	v_exp_f32_e32 v140, v140
	v_exp_f32_e32 v141, v141
	v_exp_f32_e32 v142, v142
	v_exp_f32_e32 v143, v143
	v_exp_f32_e32 v144, v144
	v_exp_f32_e32 v145, v145
	v_exp_f32_e32 v146, v146
	v_add_f32_e32 v140, 1.0, v140
	v_add_f32_e32 v141, 1.0, v141
	v_add_f32_e32 v142, 1.0, v142
	v_add_f32_e32 v143, 1.0, v143
	v_add_f32_e32 v147, 1.0, v144
	v_add_f32_e32 v144, 1.0, v145
	v_add_f32_e32 v145, 1.0, v146
	v_rcp_f32_e32 v140, v140
	v_rcp_f32_e32 v141, v141
	v_rcp_f32_e32 v142, v142
	v_rcp_f32_e32 v143, v143
	v_rcp_f32_e32 v144, v144
	v_rcp_f32_e32 v145, v145
	v_rcp_f32_e32 v149, v147
	v_pk_mul_f32 v[142:143], v[46:47], v[142:143]
	v_pk_mul_f32 v[146:147], v[44:45], v[140:141]
	v_pk_mul_f32 v[144:145], v[42:43], v[144:145]
	v_pk_mul_f32 v[148:149], v[40:41], v[148:149]
.LBB0_318:
	v_add_u32_e32 v156, 0x90, v155
	v_mov_b64_e32 v[140:141], s[74:75]
	v_mad_i64_i32 v[140:141], s[20:21], v156, s97, v[140:141]
	v_lshl_add_u64 v[140:141], v[172:173], 1, v[140:141]
	v_cvt_pk_bf16_f32 v146, v146, v147
	v_cvt_pk_bf16_f32 v147, v142, v143
	v_cvt_pk_bf16_f32 v148, v148, v149
	v_cvt_pk_bf16_f32 v149, v144, v145
	s_cmp_eq_u32 s34, 4
	s_cbranch_scc1 .Lwt3_18
	global_store_dwordx4 v[140:141], v[146:149], off
	s_branch .Lwj3_18

; __device__ __forceinline__ unsigned cvt_pk_bf16(float lo, float hi) { unsigned r; asm volatile("v_cvt_pk_bf16_f32 %0, %1, %2" : "=v"(r) : "v"(lo), "v"(hi)); return r; }
; __device__ __forceinline__ float silu_f(float v) { return v * __builtin_amdgcn_rcpf(1.0f + __builtin_amdgcn_exp2f(-v * LOG2E_)); }
;     __device__ __forceinline__ void operator()(const f32x4 (&acc)[2][2][4][2], const Unit& u, int wr, int wc, int fr, int fq) const {
;     ...
;                     for (int bj = 0; bj < 2; ++bj) { f32x4 v0 = acc[ai][bj][m][0], v1 = acc[ai][bj][m][1];
;                         if (za) { v0 = (f32x4){silu_f(v0[0]), silu_f(v0[1]), silu_f(v0[2]), silu_f(v0[3])}; v1 = (f32x4){silu_f(v1[0]), silu_f(v1[1]), silu_f(v1[2]), silu_f(v1[3])}; }
;                         u32x4 w; w.x = cvt_pk_bf16(v0[0], v0[1]); w.y = cvt_pk_bf16(v0[2], v0[3]); w.z = cvt_pk_bf16(v1[0], v1[1]); w.w = cvt_pk_bf16(v1[2], v1[3]);
;                         *(u32x4*)(rowp + bj * HALF) = w; } }
.Lwj3_18:
	s_and_b64 vcc, exec, s[4:5]
	v_mov_b32_e32 v145, v35
	v_mov_b32_e32 v144, v34
	v_mov_b32_e32 v149, v33
	v_mov_b32_e32 v148, v32
	v_mov_b32_e32 v143, v39
	v_mov_b32_e32 v142, v38
	v_mov_b32_e32 v147, v37
	v_mov_b32_e32 v146, v36
	s_cbranch_vccnz .LBB0_320
	v_mul_f32_e32 v142, 0xbfb8aa3b, v36
	v_exp_f32_e32 v142, v142
	v_mul_f32_e32 v143, 0xbfb8aa3b, v37
	v_mul_f32_e32 v144, 0xbfb8aa3b, v38
	v_exp_f32_e32 v143, v143
	v_exp_f32_e32 v146, v144
	v_add_f32_e32 v142, 1.0, v142
	v_rcp_f32_e32 v144, v142
	v_add_f32_e32 v142, 1.0, v143
	v_rcp_f32_e32 v145, v142
	v_add_f32_e32 v142, 1.0, v146
	v_mul_f32_e32 v146, 0xbfb8aa3b, v32
	v_exp_f32_e32 v146, v146
	v_mul_f32_e32 v147, 0xbfb8aa3b, v34
	v_mul_f32_e32 v143, 0xbfb8aa3b, v39
	v_exp_f32_e32 v147, v147
	v_add_f32_e32 v146, 1.0, v146
	v_rcp_f32_e32 v148, v146
	v_mul_f32_e32 v146, 0xbfb8aa3b, v33
	v_mul_f32_e32 v149, 0xbfb8aa3b, v35
	v_exp_f32_e32 v143, v143
	v_exp_f32_e32 v146, v146
	v_exp_f32_e32 v149, v149
	v_add_f32_e32 v147, 1.0, v147
	v_add_f32_e32 v143, 1.0, v143
	v_add_f32_e32 v146, 1.0, v146
	v_rcp_f32_e32 v156, v147
	v_add_f32_e32 v147, 1.0, v149
	v_rcp_f32_e32 v142, v142
	v_rcp_f32_e32 v143, v143
	v_rcp_f32_e32 v157, v147
	v_rcp_f32_e32 v149, v146
	v_pk_mul_f32 v[146:147], v[36:37], v[144:145]
	v_pk_mul_f32 v[142:143], v[38:39], v[142:143]
	v_pk_mul_f32 v[144:145], v[34:35], v[156:157]
	v_pk_mul_f32 v[148:149], v[32:33], v[148:149]

; __device__ __forceinline__ unsigned cvt_pk_bf16(float lo, float hi) { unsigned r; asm volatile("v_cvt_pk_bf16_f32 %0, %1, %2" : "=v"(r) : "v"(lo), "v"(hi)); return r; }
; __device__ __forceinline__ float silu_f(float v) { return v * __builtin_amdgcn_rcpf(1.0f + __builtin_amdgcn_exp2f(-v * LOG2E_)); }
;     __device__ __forceinline__ void operator()(const f32x4 (&acc)[2][2][4][2], const Unit& u, int wr, int wc, int fr, int fq) const {
;     ...
;                 for (int m = 0; m < 4; ++m) { bf16_t* rowp = O + (size_t)(row0 + ai * HALF + m * 16) * PO2 + col0;
; #pragma unroll
;                     for (int bj = 0; bj < 2; ++bj) { f32x4 v0 = acc[ai][bj][m][0], v1 = acc[ai][bj][m][1];
;                         if (za) { v0 = (f32x4){silu_f(v0[0]), silu_f(v0[1]), silu_f(v0[2]), silu_f(v0[3])}; v1 = (f32x4){silu_f(v1[0]), silu_f(v1[1]), silu_f(v1[2]), silu_f(v1[3])}; }
;                         u32x4 w; w.x = cvt_pk_bf16(v0[0], v0[1]); w.y = cvt_pk_bf16(v0[2], v0[3]); w.z = cvt_pk_bf16(v1[0], v1[1]); w.w = cvt_pk_bf16(v1[2], v1[3]);
;                         *(u32x4*)(rowp + bj * HALF) = w; } }
.Lwj3_19:
	s_and_b64 vcc, exec, s[4:5]
	v_mov_b32_e32 v145, v27
	v_mov_b32_e32 v144, v26
	v_mov_b32_e32 v149, v25
	v_mov_b32_e32 v148, v24
	v_mov_b32_e32 v143, v31
	v_mov_b32_e32 v142, v30
	v_mov_b32_e32 v147, v29
	v_mov_b32_e32 v146, v28
	s_cbranch_vccnz .LBB0_322
	v_mul_f32_e32 v144, 0xbfb8aa3b, v24
	v_exp_f32_e32 v144, v144
	v_mul_f32_e32 v140, 0xbfb8aa3b, v28
	v_mul_f32_e32 v141, 0xbfb8aa3b, v29
	v_mul_f32_e32 v142, 0xbfb8aa3b, v30
	v_add_f32_e32 v144, 1.0, v144
	v_mul_f32_e32 v143, 0xbfb8aa3b, v31
	v_rcp_f32_e32 v148, v144
	v_mul_f32_e32 v144, 0xbfb8aa3b, v25
	v_mul_f32_e32 v145, 0xbfb8aa3b, v26
	v_mul_f32_e32 v146, 0xbfb8aa3b, v27
	v_exp_f32_e32 v140, v140
	v_exp_f32_e32 v141, v141
	v_exp_f32_e32 v142, v142
	v_exp_f32_e32 v143, v143
	v_exp_f32_e32 v144, v144
	v_exp_f32_e32 v145, v145
	v_exp_f32_e32 v146, v146
	v_add_f32_e32 v140, 1.0, v140
	v_add_f32_e32 v141, 1.0, v141
	v_add_f32_e32 v142, 1.0, v142
	v_add_f32_e32 v143, 1.0, v143
	v_add_f32_e32 v147, 1.0, v144
	v_add_f32_e32 v144, 1.0, v145
	v_add_f32_e32 v145, 1.0, v146
	v_rcp_f32_e32 v140, v140
	v_rcp_f32_e32 v141, v141
	v_rcp_f32_e32 v142, v142
	v_rcp_f32_e32 v143, v143
	v_rcp_f32_e32 v144, v144
	v_rcp_f32_e32 v145, v145
	v_rcp_f32_e32 v149, v147
	v_pk_mul_f32 v[142:143], v[30:31], v[142:143]
	v_pk_mul_f32 v[146:147], v[28:29], v[140:141]
	v_pk_mul_f32 v[144:145], v[26:27], v[144:145]
	v_pk_mul_f32 v[148:149], v[24:25], v[148:149]
.LBB0_322:
	v_add_u32_e32 v156, 0xa0, v155
	v_mov_b64_e32 v[140:141], s[74:75]
	v_mad_i64_i32 v[140:141], s[20:21], v156, s97, v[140:141]
	v_lshl_add_u64 v[140:141], v[172:173], 1, v[140:141]
	v_cvt_pk_bf16_f32 v146, v146, v147
	v_cvt_pk_bf16_f32 v147, v142, v143
	v_cvt_pk_bf16_f32 v148, v148, v149
	v_cvt_pk_bf16_f32 v149, v144, v145
	s_cmp_eq_u32 s34, 4
	s_cbranch_scc1 .Lwt3_20
	global_store_dwordx4 v[140:141], v[146:149], off
	s_branch .Lwj3_20

; __device__ __forceinline__ unsigned cvt_pk_bf16(float lo, float hi) { unsigned r; asm volatile("v_cvt_pk_bf16_f32 %0, %1, %2" : "=v"(r) : "v"(lo), "v"(hi)); return r; }
; __device__ __forceinline__ float silu_f(float v) { return v * __builtin_amdgcn_rcpf(1.0f + __builtin_amdgcn_exp2f(-v * LOG2E_)); }
;     __device__ __forceinline__ void operator()(const f32x4 (&acc)[2][2][4][2], const Unit& u, int wr, int wc, int fr, int fq) const {
;     ...
;                     for (int bj = 0; bj < 2; ++bj) { f32x4 v0 = acc[ai][bj][m][0], v1 = acc[ai][bj][m][1];
;                         if (za) { v0 = (f32x4){silu_f(v0[0]), silu_f(v0[1]), silu_f(v0[2]), silu_f(v0[3])}; v1 = (f32x4){silu_f(v1[0]), silu_f(v1[1]), silu_f(v1[2]), silu_f(v1[3])}; }
;                         u32x4 w; w.x = cvt_pk_bf16(v0[0], v0[1]); w.y = cvt_pk_bf16(v0[2], v0[3]); w.z = cvt_pk_bf16(v1[0], v1[1]); w.w = cvt_pk_bf16(v1[2], v1[3]);
;                         *(u32x4*)(rowp + bj * HALF) = w; } }
.Lwj3_20:
	s_and_b64 vcc, exec, s[4:5]
	v_mov_b32_e32 v145, v19
	v_mov_b32_e32 v144, v18
	v_mov_b32_e32 v149, v17
	v_mov_b32_e32 v148, v16
	v_mov_b32_e32 v143, v23
	v_mov_b32_e32 v142, v22
	v_mov_b32_e32 v147, v21
	v_mov_b32_e32 v146, v20
	s_cbranch_vccnz .LBB0_324
	v_mul_f32_e32 v142, 0xbfb8aa3b, v20
	v_exp_f32_e32 v142, v142
	v_mul_f32_e32 v143, 0xbfb8aa3b, v21
	v_mul_f32_e32 v144, 0xbfb8aa3b, v22
	v_exp_f32_e32 v143, v143
	v_exp_f32_e32 v146, v144
	v_add_f32_e32 v142, 1.0, v142
	v_rcp_f32_e32 v144, v142
	v_add_f32_e32 v142, 1.0, v143
	v_rcp_f32_e32 v145, v142
	v_add_f32_e32 v142, 1.0, v146
	v_mul_f32_e32 v146, 0xbfb8aa3b, v16
	v_exp_f32_e32 v146, v146
	v_mul_f32_e32 v147, 0xbfb8aa3b, v18
	v_mul_f32_e32 v143, 0xbfb8aa3b, v23
	v_exp_f32_e32 v147, v147
	v_add_f32_e32 v146, 1.0, v146
	v_rcp_f32_e32 v148, v146
	v_mul_f32_e32 v146, 0xbfb8aa3b, v17
	v_mul_f32_e32 v149, 0xbfb8aa3b, v19
	v_exp_f32_e32 v143, v143
	v_exp_f32_e32 v146, v146
	v_exp_f32_e32 v149, v149
	v_add_f32_e32 v147, 1.0, v147
	v_add_f32_e32 v143, 1.0, v143
	v_add_f32_e32 v146, 1.0, v146
	v_rcp_f32_e32 v156, v147
	v_add_f32_e32 v147, 1.0, v149
	v_rcp_f32_e32 v142, v142
	v_rcp_f32_e32 v143, v143
	v_rcp_f32_e32 v157, v147
	v_rcp_f32_e32 v149, v146
	v_pk_mul_f32 v[146:147], v[20:21], v[144:145]
	v_pk_mul_f32 v[142:143], v[22:23], v[142:143]
	v_pk_mul_f32 v[144:145], v[18:19], v[156:157]
	v_pk_mul_f32 v[148:149], v[16:17], v[148:149]

; __device__ __forceinline__ unsigned cvt_pk_bf16(float lo, float hi) { unsigned r; asm volatile("v_cvt_pk_bf16_f32 %0, %1, %2" : "=v"(r) : "v"(lo), "v"(hi)); return r; }
; __device__ __forceinline__ float silu_f(float v) { return v * __builtin_amdgcn_rcpf(1.0f + __builtin_amdgcn_exp2f(-v * LOG2E_)); }
;     __device__ __forceinline__ void operator()(const f32x4 (&acc)[2][2][4][2], const Unit& u, int wr, int wc, int fr, int fq) const {
;     ...
;                 for (int m = 0; m < 4; ++m) { bf16_t* rowp = O + (size_t)(row0 + ai * HALF + m * 16) * PO2 + col0;
; #pragma unroll
;                     for (int bj = 0; bj < 2; ++bj) { f32x4 v0 = acc[ai][bj][m][0], v1 = acc[ai][bj][m][1];
;                         if (za) { v0 = (f32x4){silu_f(v0[0]), silu_f(v0[1]), silu_f(v0[2]), silu_f(v0[3])}; v1 = (f32x4){silu_f(v1[0]), silu_f(v1[1]), silu_f(v1[2]), silu_f(v1[3])}; }
;                         u32x4 w; w.x = cvt_pk_bf16(v0[0], v0[1]); w.y = cvt_pk_bf16(v0[2], v0[3]); w.z = cvt_pk_bf16(v1[0], v1[1]); w.w = cvt_pk_bf16(v1[2], v1[3]);
;                         *(u32x4*)(rowp + bj * HALF) = w; } }
.Lwj3_21:
	s_and_b64 vcc, exec, s[4:5]
	v_mov_b32_e32 v145, v11
	v_mov_b32_e32 v144, v10
	v_mov_b32_e32 v149, v9
	v_mov_b32_e32 v148, v8
	v_mov_b32_e32 v143, v15
	v_mov_b32_e32 v142, v14
	v_mov_b32_e32 v147, v13
	v_mov_b32_e32 v146, v12
	s_cbranch_vccnz .LBB0_326
	v_mul_f32_e32 v144, 0xbfb8aa3b, v8
	v_exp_f32_e32 v144, v144
	v_mul_f32_e32 v140, 0xbfb8aa3b, v12
	v_mul_f32_e32 v141, 0xbfb8aa3b, v13
	v_mul_f32_e32 v142, 0xbfb8aa3b, v14
	v_add_f32_e32 v144, 1.0, v144
	v_mul_f32_e32 v143, 0xbfb8aa3b, v15
	v_rcp_f32_e32 v148, v144
	v_mul_f32_e32 v144, 0xbfb8aa3b, v9
	v_mul_f32_e32 v145, 0xbfb8aa3b, v10
	v_mul_f32_e32 v146, 0xbfb8aa3b, v11
	v_exp_f32_e32 v140, v140
	v_exp_f32_e32 v141, v141
	v_exp_f32_e32 v142, v142
	v_exp_f32_e32 v143, v143
	v_exp_f32_e32 v144, v144
	v_exp_f32_e32 v145, v145
	v_exp_f32_e32 v146, v146
	v_add_f32_e32 v140, 1.0, v140
	v_add_f32_e32 v141, 1.0, v141
	v_add_f32_e32 v142, 1.0, v142
	v_add_f32_e32 v143, 1.0, v143
	v_add_f32_e32 v147, 1.0, v144
	v_add_f32_e32 v144, 1.0, v145
	v_add_f32_e32 v145, 1.0, v146
	v_rcp_f32_e32 v140, v140
	v_rcp_f32_e32 v141, v141
	v_rcp_f32_e32 v142, v142
	v_rcp_f32_e32 v143, v143
	v_rcp_f32_e32 v144, v144
	v_rcp_f32_e32 v145, v145
	v_rcp_f32_e32 v149, v147
	v_pk_mul_f32 v[142:143], v[14:15], v[142:143]
	v_pk_mul_f32 v[146:147], v[12:13], v[140:141]
	v_pk_mul_f32 v[144:145], v[10:11], v[144:145]
	v_pk_mul_f32 v[148:149], v[8:9], v[148:149]
.LBB0_326:
	v_add_u32_e32 v156, 0xb0, v155
	v_mov_b64_e32 v[140:141], s[74:75]
	v_mad_i64_i32 v[140:141], s[20:21], v156, s97, v[140:141]
	v_lshl_add_u64 v[140:141], v[172:173], 1, v[140:141]
	v_cvt_pk_bf16_f32 v146, v146, v147
	v_cvt_pk_bf16_f32 v147, v142, v143
	v_cvt_pk_bf16_f32 v148, v148, v149
	v_cvt_pk_bf16_f32 v149, v144, v145
	s_cmp_eq_u32 s34, 4
	s_cbranch_scc1 .Lwt3_22
	global_store_dwordx4 v[140:141], v[146:149], off
	s_branch .Lwj3_22

; __device__ __forceinline__ unsigned cvt_pk_bf16(float lo, float hi) { unsigned r; asm volatile("v_cvt_pk_bf16_f32 %0, %1, %2" : "=v"(r) : "v"(lo), "v"(hi)); return r; }
; __device__ __forceinline__ float silu_f(float v) { return v * __builtin_amdgcn_rcpf(1.0f + __builtin_amdgcn_exp2f(-v * LOG2E_)); }
;     __device__ __forceinline__ void operator()(const f32x4 (&acc)[2][2][4][2], const Unit& u, int wr, int wc, int fr, int fq) const {
;     ...
;                     for (int bj = 0; bj < 2; ++bj) { f32x4 v0 = acc[ai][bj][m][0], v1 = acc[ai][bj][m][1];
;                         if (za) { v0 = (f32x4){silu_f(v0[0]), silu_f(v0[1]), silu_f(v0[2]), silu_f(v0[3])}; v1 = (f32x4){silu_f(v1[0]), silu_f(v1[1]), silu_f(v1[2]), silu_f(v1[3])}; }
;                         u32x4 w; w.x = cvt_pk_bf16(v0[0], v0[1]); w.y = cvt_pk_bf16(v0[2], v0[3]); w.z = cvt_pk_bf16(v1[0], v1[1]); w.w = cvt_pk_bf16(v1[2], v1[3]);
;                         *(u32x4*)(rowp + bj * HALF) = w; } }
;         }
.Lwj3_22:
	s_and_b64 vcc, exec, s[4:5]
	v_mov_b32_e32 v143, v3
	v_mov_b32_e32 v142, v2
	v_mov_b32_e32 v147, v1
	v_mov_b32_e32 v146, v0
	v_mov_b32_e32 v145, v7
	v_mov_b32_e32 v144, v6
	v_mov_b32_e32 v149, v5
	v_mov_b32_e32 v148, v4
	s_cbranch_vccnz .LBB0_328
	v_mul_f32_e32 v148, 0xbfb8aa3b, v2
	v_mul_f32_e32 v142, 0xbfb8aa3b, v4
	v_mul_f32_e32 v143, 0xbfb8aa3b, v5
	v_mul_f32_e32 v144, 0xbfb8aa3b, v6
	v_mul_f32_e32 v145, 0xbfb8aa3b, v7
	v_mul_f32_e32 v146, 0xbfb8aa3b, v0
	v_mul_f32_e32 v147, 0xbfb8aa3b, v1
	v_exp_f32_e32 v148, v148
	v_mul_f32_e32 v149, 0xbfb8aa3b, v3
	v_exp_f32_e32 v142, v142
	v_exp_f32_e32 v143, v143
	v_exp_f32_e32 v144, v144
	v_exp_f32_e32 v145, v145
	v_exp_f32_e32 v146, v146
	v_exp_f32_e32 v147, v147
	v_exp_f32_e32 v149, v149
	v_add_f32_e32 v148, 1.0, v148
	v_add_f32_e32 v142, 1.0, v142
	v_add_f32_e32 v143, 1.0, v143
	v_add_f32_e32 v144, 1.0, v144
	v_add_f32_e32 v145, 1.0, v145
	v_add_f32_e32 v146, 1.0, v146
	v_add_f32_e32 v147, 1.0, v147
	v_rcp_f32_e32 v156, v148
	v_add_f32_e32 v148, 1.0, v149
	v_rcp_f32_e32 v142, v142
	v_rcp_f32_e32 v143, v143
	v_rcp_f32_e32 v144, v144
	v_rcp_f32_e32 v145, v145
	v_rcp_f32_e32 v146, v146
	v_rcp_f32_e32 v157, v148
	v_rcp_f32_e32 v147, v147
	v_pk_mul_f32 v[144:145], v[6:7], v[144:145]
	v_pk_mul_f32 v[148:149], v[4:5], v[142:143]
	v_pk_mul_f32 v[142:143], v[2:3], v[156:157]
	v_pk_mul_f32 v[146:147], v[0:1], v[146:147]
.LBB0_328:
	v_cvt_pk_bf16_f32 v156, v148, v149
	v_cvt_pk_bf16_f32 v157, v144, v145
	s_nop 0
	v_cvt_pk_bf16_f32 v158, v146, v147
	v_cvt_pk_bf16_f32 v159, v142, v143
	s_cmp_eq_u32 s34, 4
	s_cbranch_scc1 .Lwt3_23
	global_store_dwordx4 v[140:141], v[156:159], off offset:256
	s_branch .Lwj3_23
.Lwt3_23:
	global_store_dwordx4 v[140:141], v[156:159], off offset:256 sc1
.Lwj3_23:
.LBB0_329:
	s_andn2_b64 vcc, exec, s[0:1]
	s_mov_b64 s[0:1], -1
	s_cbranch_vccnz .LBB0_266
